# non-temporal hint also on the once-read residual loads of both out-projection epilogues
# speedup vs baseline: 1.0763x; 1.0288x over previous
; #define LAS __attribute__((address_space(3)))
;     __device__ __forceinline__ void operator()(const f32x4 (&acc)[2][2][4][2], const Unit& u, int wr, int wc, int fr, int fq, LAS unsigned char*) const {
;         const int row0 = u.pm * BM + wr * 64 + fr; const int col0 = u.pn * BM + wc * 32 + 8 * fq;
; #pragma unroll
;         for (int ai = 0; ai < 2; ++ai)
; #pragma unroll
;             for (int m = 0; m < 4; ++m) { const size_t ro = (size_t)(row0 + ai * HALF + m * 16) * ldc + col0;
; #pragma unroll
;                 for (int bj = 0; bj < 2; ++bj) { const size_t o = ro + bj * HALF; const f32x4 r0 = *(const f32x4*)(res + o), r1 = *(const f32x4*)(res + o + 4);
;                     *(f32x4*)(O + o) = r0 + acc[ai][bj][m][0]; *(f32x4*)(O + o + 4) = r1 + acc[ai][bj][m][1]; } }
.LBB0_762:
	v_and_b32_e32 v176, 8, v140
	v_sub_u32_e32 v166, v140, v176
	v_lshl_add_u32 v166, s39, 8, v166
	v_mov_b32_e32 v167, 0
	v_lshlrev_b64 v[138:139], 12, v[166:167]
	v_lshl_add_u64 v[138:139], s[76:77], 0, v[138:139]
	v_lshl_or_b32 v166, s5, 8, v142
	v_lshlrev_b32_e32 v166, 2, v166
	v_lshl_add_u32 v166, v176, 1, v166
	v_lshl_add_u64 v[138:139], v[138:139], 0, v[166:167]
	s_mov_b64 s[16:17], 0x8000
	s_mov_b64 s[18:19], 0x10000
	s_mov_b64 s[40:41], 0x50000
	v_lshl_add_u64 v[160:161], v[138:139], 0, s[16:17]
	v_mov_b64_e32 v[162:163], v[138:139]
	v_mov_b64_e32 v[164:165], v[160:161]
	global_load_dwordx4 v[196:199], v[138:139], off nt
	global_load_dwordx4 v[200:203], v[138:139], off offset:512 nt
	global_load_dwordx4 v[204:207], v[160:161], off nt
	global_load_dwordx4 v[208:211], v[160:161], off offset:512 nt
	v_lshl_add_u64 v[138:139], v[138:139], 0, s[18:19]
	v_lshl_add_u64 v[160:161], v[160:161], 0, s[18:19]
	global_load_dwordx4 v[212:215], v[138:139], off nt
	global_load_dwordx4 v[216:219], v[138:139], off offset:512 nt
	global_load_dwordx4 v[220:223], v[160:161], off nt
	global_load_dwordx4 v[224:227], v[160:161], off offset:512 nt
	v_lshl_add_u64 v[138:139], v[138:139], 0, s[18:19]
	v_lshl_add_u64 v[160:161], v[160:161], 0, s[18:19]
	global_load_dwordx4 v[228:231], v[138:139], off nt
	global_load_dwordx4 v[232:235], v[138:139], off offset:512 nt
	global_load_dwordx4 v[236:239], v[160:161], off nt
	global_load_dwordx4 v[240:243], v[160:161], off offset:512 nt
	v_lshl_add_u64 v[138:139], v[138:139], 0, s[18:19]
	v_lshl_add_u64 v[160:161], v[160:161], 0, s[18:19]
	global_load_dwordx4 v[168:171], v[138:139], off nt
	global_load_dwordx4 v[172:175], v[138:139], off offset:512 nt
	global_load_dwordx4 v[180:183], v[160:161], off nt
	global_load_dwordx4 v[156:159], v[160:161], off offset:512 nt
	v_lshl_add_u64 v[138:139], v[138:139], 0, s[40:41]
	v_lshl_add_u64 v[160:161], v[160:161], 0, s[40:41]
	v_mov_b32_dpp v176, v124 row_ror:8 row_mask:0xf bank_mask:0xf
	v_mov_b32_dpp v177, v125 row_ror:8 row_mask:0xf bank_mask:0xf
	v_mov_b32_dpp v124, v120 row_ror:8 row_mask:0xf bank_mask:0xc
	v_mov_b32_dpp v125, v121 row_ror:8 row_mask:0xf bank_mask:0xc
	v_mov_b32_dpp v120, v176 quad_perm:[0,1,2,3] row_mask:0xf bank_mask:0x3
	v_mov_b32_dpp v121, v177 quad_perm:[0,1,2,3] row_mask:0xf bank_mask:0x3
	v_mov_b32_dpp v176, v126 row_ror:8 row_mask:0xf bank_mask:0xf
	v_mov_b32_dpp v177, v127 row_ror:8 row_mask:0xf bank_mask:0xf
	v_mov_b32_dpp v126, v122 row_ror:8 row_mask:0xf bank_mask:0xc
	v_mov_b32_dpp v127, v123 row_ror:8 row_mask:0xf bank_mask:0xc
	v_mov_b32_dpp v122, v176 quad_perm:[0,1,2,3] row_mask:0xf bank_mask:0x3
	v_mov_b32_dpp v123, v177 quad_perm:[0,1,2,3] row_mask:0xf bank_mask:0x3
	v_mov_b32_dpp v176, v116 row_ror:8 row_mask:0xf bank_mask:0xf
	v_mov_b32_dpp v177, v117 row_ror:8 row_mask:0xf bank_mask:0xf
	v_mov_b32_dpp v116, v112 row_ror:8 row_mask:0xf bank_mask:0xc
	v_mov_b32_dpp v117, v113 row_ror:8 row_mask:0xf bank_mask:0xc
	v_mov_b32_dpp v112, v176 quad_perm:[0,1,2,3] row_mask:0xf bank_mask:0x3
	v_mov_b32_dpp v113, v177 quad_perm:[0,1,2,3] row_mask:0xf bank_mask:0x3
	v_mov_b32_dpp v176, v118 row_ror:8 row_mask:0xf bank_mask:0xf
	v_mov_b32_dpp v177, v119 row_ror:8 row_mask:0xf bank_mask:0xf
	v_mov_b32_dpp v118, v114 row_ror:8 row_mask:0xf bank_mask:0xc
	v_mov_b32_dpp v119, v115 row_ror:8 row_mask:0xf bank_mask:0xc
	v_mov_b32_dpp v114, v176 quad_perm:[0,1,2,3] row_mask:0xf bank_mask:0x3
	v_mov_b32_dpp v115, v177 quad_perm:[0,1,2,3] row_mask:0xf bank_mask:0x3
	v_mov_b32_dpp v176, v108 row_ror:8 row_mask:0xf bank_mask:0xf
	v_mov_b32_dpp v177, v109 row_ror:8 row_mask:0xf bank_mask:0xf
	v_mov_b32_dpp v108, v104 row_ror:8 row_mask:0xf bank_mask:0xc
	v_mov_b32_dpp v109, v105 row_ror:8 row_mask:0xf bank_mask:0xc
	v_mov_b32_dpp v104, v176 quad_perm:[0,1,2,3] row_mask:0xf bank_mask:0x3
	v_mov_b32_dpp v105, v177 quad_perm:[0,1,2,3] row_mask:0xf bank_mask:0x3
	v_mov_b32_dpp v176, v110 row_ror:8 row_mask:0xf bank_mask:0xf
	v_mov_b32_dpp v177, v111 row_ror:8 row_mask:0xf bank_mask:0xf
	v_mov_b32_dpp v110, v106 row_ror:8 row_mask:0xf bank_mask:0xc
	v_mov_b32_dpp v111, v107 row_ror:8 row_mask:0xf bank_mask:0xc
	v_mov_b32_dpp v106, v176 quad_perm:[0,1,2,3] row_mask:0xf bank_mask:0x3
	v_mov_b32_dpp v107, v177 quad_perm:[0,1,2,3] row_mask:0xf bank_mask:0x3
	v_mov_b32_dpp v176, v92 row_ror:8 row_mask:0xf bank_mask:0xf
	v_mov_b32_dpp v177, v93 row_ror:8 row_mask:0xf bank_mask:0xf
	v_mov_b32_dpp v92, v88 row_ror:8 row_mask:0xf bank_mask:0xc
	v_mov_b32_dpp v93, v89 row_ror:8 row_mask:0xf bank_mask:0xc
	v_mov_b32_dpp v88, v176 quad_perm:[0,1,2,3] row_mask:0xf bank_mask:0x3
	v_mov_b32_dpp v89, v177 quad_perm:[0,1,2,3] row_mask:0xf bank_mask:0x3
	v_mov_b32_dpp v176, v94 row_ror:8 row_mask:0xf bank_mask:0xf
	v_mov_b32_dpp v177, v95 row_ror:8 row_mask:0xf bank_mask:0xf
	v_mov_b32_dpp v94, v90 row_ror:8 row_mask:0xf bank_mask:0xc
	v_mov_b32_dpp v95, v91 row_ror:8 row_mask:0xf bank_mask:0xc
	v_mov_b32_dpp v90, v176 quad_perm:[0,1,2,3] row_mask:0xf bank_mask:0x3
	v_mov_b32_dpp v91, v177 quad_perm:[0,1,2,3] row_mask:0xf bank_mask:0x3
	v_mov_b32_dpp v176, v100 row_ror:8 row_mask:0xf bank_mask:0xf
	v_mov_b32_dpp v177, v101 row_ror:8 row_mask:0xf bank_mask:0xf
	v_mov_b32_dpp v100, v96 row_ror:8 row_mask:0xf bank_mask:0xc
	v_mov_b32_dpp v101, v97 row_ror:8 row_mask:0xf bank_mask:0xc
	v_mov_b32_dpp v96, v176 quad_perm:[0,1,2,3] row_mask:0xf bank_mask:0x3
	v_mov_b32_dpp v97, v177 quad_perm:[0,1,2,3] row_mask:0xf bank_mask:0x3
	v_mov_b32_dpp v176, v102 row_ror:8 row_mask:0xf bank_mask:0xf
	v_mov_b32_dpp v177, v103 row_ror:8 row_mask:0xf bank_mask:0xf
; #define LAS __attribute__((address_space(3)))
;     __device__ __forceinline__ void operator()(const f32x4 (&acc)[2][2][4][2], const Unit& u, int wr, int wc, int fr, int fq, LAS unsigned char*) const {
;         const int row0 = u.pm * BM + wr * 64 + fr; const int col0 = u.pn * BM + wc * 32 + 8 * fq;
; #pragma unroll
;         for (int ai = 0; ai < 2; ++ai)
; #pragma unroll
;             for (int m = 0; m < 4; ++m) { const size_t ro = (size_t)(row0 + ai * HALF + m * 16) * ldc + col0;
; #pragma unroll
;                 for (int bj = 0; bj < 2; ++bj) { const size_t o = ro + bj * HALF; const f32x4 r0 = *(const f32x4*)(res + o), r1 = *(const f32x4*)(res + o + 4);
;                     *(f32x4*)(O + o) = r0 + acc[ai][bj][m][0]; *(f32x4*)(O + o + 4) = r1 + acc[ai][bj][m][1]; } }
	v_mov_b32_dpp v102, v98 row_ror:8 row_mask:0xf bank_mask:0xc
	v_mov_b32_dpp v103, v99 row_ror:8 row_mask:0xf bank_mask:0xc
	v_mov_b32_dpp v98, v176 quad_perm:[0,1,2,3] row_mask:0xf bank_mask:0x3
	v_mov_b32_dpp v99, v177 quad_perm:[0,1,2,3] row_mask:0xf bank_mask:0x3
	v_mov_b32_dpp v176, v76 row_ror:8 row_mask:0xf bank_mask:0xf
	v_mov_b32_dpp v177, v77 row_ror:8 row_mask:0xf bank_mask:0xf
	v_mov_b32_dpp v76, v72 row_ror:8 row_mask:0xf bank_mask:0xc
	v_mov_b32_dpp v77, v73 row_ror:8 row_mask:0xf bank_mask:0xc
	v_mov_b32_dpp v72, v176 quad_perm:[0,1,2,3] row_mask:0xf bank_mask:0x3
	v_mov_b32_dpp v73, v177 quad_perm:[0,1,2,3] row_mask:0xf bank_mask:0x3
	v_mov_b32_dpp v176, v78 row_ror:8 row_mask:0xf bank_mask:0xf
	v_mov_b32_dpp v177, v79 row_ror:8 row_mask:0xf bank_mask:0xf
	v_mov_b32_dpp v78, v74 row_ror:8 row_mask:0xf bank_mask:0xc
	v_mov_b32_dpp v79, v75 row_ror:8 row_mask:0xf bank_mask:0xc
	v_mov_b32_dpp v74, v176 quad_perm:[0,1,2,3] row_mask:0xf bank_mask:0x3
	v_mov_b32_dpp v75, v177 quad_perm:[0,1,2,3] row_mask:0xf bank_mask:0x3
	v_mov_b32_dpp v176, v84 row_ror:8 row_mask:0xf bank_mask:0xf
	v_mov_b32_dpp v177, v85 row_ror:8 row_mask:0xf bank_mask:0xf
	v_mov_b32_dpp v84, v80 row_ror:8 row_mask:0xf bank_mask:0xc
	v_mov_b32_dpp v85, v81 row_ror:8 row_mask:0xf bank_mask:0xc
	v_mov_b32_dpp v80, v176 quad_perm:[0,1,2,3] row_mask:0xf bank_mask:0x3
	v_mov_b32_dpp v81, v177 quad_perm:[0,1,2,3] row_mask:0xf bank_mask:0x3
	v_mov_b32_dpp v176, v86 row_ror:8 row_mask:0xf bank_mask:0xf
	v_mov_b32_dpp v177, v87 row_ror:8 row_mask:0xf bank_mask:0xf
	v_mov_b32_dpp v86, v82 row_ror:8 row_mask:0xf bank_mask:0xc
	v_mov_b32_dpp v87, v83 row_ror:8 row_mask:0xf bank_mask:0xc
	v_mov_b32_dpp v82, v176 quad_perm:[0,1,2,3] row_mask:0xf bank_mask:0x3
	v_mov_b32_dpp v83, v177 quad_perm:[0,1,2,3] row_mask:0xf bank_mask:0x3
	v_mov_b32_dpp v176, v68 row_ror:8 row_mask:0xf bank_mask:0xf
	v_mov_b32_dpp v177, v69 row_ror:8 row_mask:0xf bank_mask:0xf
	v_mov_b32_dpp v68, v64 row_ror:8 row_mask:0xf bank_mask:0xc
	v_mov_b32_dpp v69, v65 row_ror:8 row_mask:0xf bank_mask:0xc
	v_mov_b32_dpp v64, v176 quad_perm:[0,1,2,3] row_mask:0xf bank_mask:0x3
	v_mov_b32_dpp v65, v177 quad_perm:[0,1,2,3] row_mask:0xf bank_mask:0x3
	v_mov_b32_dpp v176, v70 row_ror:8 row_mask:0xf bank_mask:0xf
	v_mov_b32_dpp v177, v71 row_ror:8 row_mask:0xf bank_mask:0xf
	v_mov_b32_dpp v70, v66 row_ror:8 row_mask:0xf bank_mask:0xc
	v_mov_b32_dpp v71, v67 row_ror:8 row_mask:0xf bank_mask:0xc
	v_mov_b32_dpp v66, v176 quad_perm:[0,1,2,3] row_mask:0xf bank_mask:0x3
	v_mov_b32_dpp v67, v177 quad_perm:[0,1,2,3] row_mask:0xf bank_mask:0x3
	v_mov_b32_dpp v176, v60 row_ror:8 row_mask:0xf bank_mask:0xf
	v_mov_b32_dpp v177, v61 row_ror:8 row_mask:0xf bank_mask:0xf
	v_mov_b32_dpp v60, v56 row_ror:8 row_mask:0xf bank_mask:0xc
	v_mov_b32_dpp v61, v57 row_ror:8 row_mask:0xf bank_mask:0xc
	v_mov_b32_dpp v56, v176 quad_perm:[0,1,2,3] row_mask:0xf bank_mask:0x3
	v_mov_b32_dpp v57, v177 quad_perm:[0,1,2,3] row_mask:0xf bank_mask:0x3
	v_mov_b32_dpp v176, v62 row_ror:8 row_mask:0xf bank_mask:0xf
	v_mov_b32_dpp v177, v63 row_ror:8 row_mask:0xf bank_mask:0xf
	v_mov_b32_dpp v62, v58 row_ror:8 row_mask:0xf bank_mask:0xc
	v_mov_b32_dpp v63, v59 row_ror:8 row_mask:0xf bank_mask:0xc
	v_mov_b32_dpp v58, v176 quad_perm:[0,1,2,3] row_mask:0xf bank_mask:0x3
	v_mov_b32_dpp v59, v177 quad_perm:[0,1,2,3] row_mask:0xf bank_mask:0x3
	v_mov_b32_dpp v176, v52 row_ror:8 row_mask:0xf bank_mask:0xf
	v_mov_b32_dpp v177, v53 row_ror:8 row_mask:0xf bank_mask:0xf
	v_mov_b32_dpp v52, v48 row_ror:8 row_mask:0xf bank_mask:0xc
	v_mov_b32_dpp v53, v49 row_ror:8 row_mask:0xf bank_mask:0xc
	v_mov_b32_dpp v48, v176 quad_perm:[0,1,2,3] row_mask:0xf bank_mask:0x3
	v_mov_b32_dpp v49, v177 quad_perm:[0,1,2,3] row_mask:0xf bank_mask:0x3
	v_mov_b32_dpp v176, v54 row_ror:8 row_mask:0xf bank_mask:0xf
	v_mov_b32_dpp v177, v55 row_ror:8 row_mask:0xf bank_mask:0xf
	v_mov_b32_dpp v54, v50 row_ror:8 row_mask:0xf bank_mask:0xc
	v_mov_b32_dpp v55, v51 row_ror:8 row_mask:0xf bank_mask:0xc
	v_mov_b32_dpp v50, v176 quad_perm:[0,1,2,3] row_mask:0xf bank_mask:0x3
	v_mov_b32_dpp v51, v177 quad_perm:[0,1,2,3] row_mask:0xf bank_mask:0x3
	v_mov_b32_dpp v176, v44 row_ror:8 row_mask:0xf bank_mask:0xf
	v_mov_b32_dpp v177, v45 row_ror:8 row_mask:0xf bank_mask:0xf
	v_mov_b32_dpp v44, v40 row_ror:8 row_mask:0xf bank_mask:0xc
	v_mov_b32_dpp v45, v41 row_ror:8 row_mask:0xf bank_mask:0xc
	v_mov_b32_dpp v40, v176 quad_perm:[0,1,2,3] row_mask:0xf bank_mask:0x3
	v_mov_b32_dpp v41, v177 quad_perm:[0,1,2,3] row_mask:0xf bank_mask:0x3
	v_mov_b32_dpp v176, v46 row_ror:8 row_mask:0xf bank_mask:0xf
	v_mov_b32_dpp v177, v47 row_ror:8 row_mask:0xf bank_mask:0xf
	v_mov_b32_dpp v46, v42 row_ror:8 row_mask:0xf bank_mask:0xc
	v_mov_b32_dpp v47, v43 row_ror:8 row_mask:0xf bank_mask:0xc
	v_mov_b32_dpp v42, v176 quad_perm:[0,1,2,3] row_mask:0xf bank_mask:0x3
	v_mov_b32_dpp v43, v177 quad_perm:[0,1,2,3] row_mask:0xf bank_mask:0x3
	v_mov_b32_dpp v176, v36 row_ror:8 row_mask:0xf bank_mask:0xf
	v_mov_b32_dpp v177, v37 row_ror:8 row_mask:0xf bank_mask:0xf
	v_mov_b32_dpp v36, v32 row_ror:8 row_mask:0xf bank_mask:0xc
	v_mov_b32_dpp v37, v33 row_ror:8 row_mask:0xf bank_mask:0xc
	v_mov_b32_dpp v32, v176 quad_perm:[0,1,2,3] row_mask:0xf bank_mask:0x3
	v_mov_b32_dpp v33, v177 quad_perm:[0,1,2,3] row_mask:0xf bank_mask:0x3
	v_mov_b32_dpp v176, v38 row_ror:8 row_mask:0xf bank_mask:0xf
	v_mov_b32_dpp v177, v39 row_ror:8 row_mask:0xf bank_mask:0xf
	v_mov_b32_dpp v38, v34 row_ror:8 row_mask:0xf bank_mask:0xc
	v_mov_b32_dpp v39, v35 row_ror:8 row_mask:0xf bank_mask:0xc
	v_mov_b32_dpp v34, v176 quad_perm:[0,1,2,3] row_mask:0xf bank_mask:0x3
;     __device__ __forceinline__ void operator()(const f32x4 (&acc)[2][2][4][2], const Unit& u, int wr, int wc, int fr, int fq, LAS unsigned char*) const {
;     ...
;             for (int m = 0; m < 4; ++m) { const size_t ro = (size_t)(row0 + ai * HALF + m * 16) * ldc + col0;
; #pragma unroll
;                 for (int bj = 0; bj < 2; ++bj) { const size_t o = ro + bj * HALF; const f32x4 r0 = *(const f32x4*)(res + o), r1 = *(const f32x4*)(res + o + 4);
;                     *(f32x4*)(O + o) = r0 + acc[ai][bj][m][0]; *(f32x4*)(O + o + 4) = r1 + acc[ai][bj][m][1]; } }
	v_mov_b32_dpp v35, v177 quad_perm:[0,1,2,3] row_mask:0xf bank_mask:0x3
	v_mov_b32_dpp v176, v28 row_ror:8 row_mask:0xf bank_mask:0xf
	v_mov_b32_dpp v177, v29 row_ror:8 row_mask:0xf bank_mask:0xf
	v_mov_b32_dpp v28, v24 row_ror:8 row_mask:0xf bank_mask:0xc
	v_mov_b32_dpp v29, v25 row_ror:8 row_mask:0xf bank_mask:0xc
	v_mov_b32_dpp v24, v176 quad_perm:[0,1,2,3] row_mask:0xf bank_mask:0x3
	v_mov_b32_dpp v25, v177 quad_perm:[0,1,2,3] row_mask:0xf bank_mask:0x3
	v_mov_b32_dpp v176, v30 row_ror:8 row_mask:0xf bank_mask:0xf
	v_mov_b32_dpp v177, v31 row_ror:8 row_mask:0xf bank_mask:0xf
	v_mov_b32_dpp v30, v26 row_ror:8 row_mask:0xf bank_mask:0xc
	v_mov_b32_dpp v31, v27 row_ror:8 row_mask:0xf bank_mask:0xc
	v_mov_b32_dpp v26, v176 quad_perm:[0,1,2,3] row_mask:0xf bank_mask:0x3
	v_mov_b32_dpp v27, v177 quad_perm:[0,1,2,3] row_mask:0xf bank_mask:0x3
	v_mov_b32_dpp v176, v20 row_ror:8 row_mask:0xf bank_mask:0xf
	v_mov_b32_dpp v177, v21 row_ror:8 row_mask:0xf bank_mask:0xf
	v_mov_b32_dpp v20, v16 row_ror:8 row_mask:0xf bank_mask:0xc
	v_mov_b32_dpp v21, v17 row_ror:8 row_mask:0xf bank_mask:0xc
	v_mov_b32_dpp v16, v176 quad_perm:[0,1,2,3] row_mask:0xf bank_mask:0x3
	v_mov_b32_dpp v17, v177 quad_perm:[0,1,2,3] row_mask:0xf bank_mask:0x3
	v_mov_b32_dpp v176, v22 row_ror:8 row_mask:0xf bank_mask:0xf
	v_mov_b32_dpp v177, v23 row_ror:8 row_mask:0xf bank_mask:0xf
	v_mov_b32_dpp v22, v18 row_ror:8 row_mask:0xf bank_mask:0xc
	v_mov_b32_dpp v23, v19 row_ror:8 row_mask:0xf bank_mask:0xc
	v_mov_b32_dpp v18, v176 quad_perm:[0,1,2,3] row_mask:0xf bank_mask:0x3
	v_mov_b32_dpp v19, v177 quad_perm:[0,1,2,3] row_mask:0xf bank_mask:0x3
	v_mov_b32_dpp v176, v12 row_ror:8 row_mask:0xf bank_mask:0xf
	v_mov_b32_dpp v177, v13 row_ror:8 row_mask:0xf bank_mask:0xf
	v_mov_b32_dpp v12, v8 row_ror:8 row_mask:0xf bank_mask:0xc
	v_mov_b32_dpp v13, v9 row_ror:8 row_mask:0xf bank_mask:0xc
	v_mov_b32_dpp v8, v176 quad_perm:[0,1,2,3] row_mask:0xf bank_mask:0x3
	v_mov_b32_dpp v9, v177 quad_perm:[0,1,2,3] row_mask:0xf bank_mask:0x3
	v_mov_b32_dpp v176, v14 row_ror:8 row_mask:0xf bank_mask:0xf
	v_mov_b32_dpp v177, v15 row_ror:8 row_mask:0xf bank_mask:0xf
	v_mov_b32_dpp v14, v10 row_ror:8 row_mask:0xf bank_mask:0xc
	v_mov_b32_dpp v15, v11 row_ror:8 row_mask:0xf bank_mask:0xc
	v_mov_b32_dpp v10, v176 quad_perm:[0,1,2,3] row_mask:0xf bank_mask:0x3
	v_mov_b32_dpp v11, v177 quad_perm:[0,1,2,3] row_mask:0xf bank_mask:0x3
	v_mov_b32_dpp v176, v4 row_ror:8 row_mask:0xf bank_mask:0xf
	v_mov_b32_dpp v177, v5 row_ror:8 row_mask:0xf bank_mask:0xf
	v_mov_b32_dpp v4, v0 row_ror:8 row_mask:0xf bank_mask:0xc
	v_mov_b32_dpp v5, v1 row_ror:8 row_mask:0xf bank_mask:0xc
	v_mov_b32_dpp v0, v176 quad_perm:[0,1,2,3] row_mask:0xf bank_mask:0x3
	v_mov_b32_dpp v1, v177 quad_perm:[0,1,2,3] row_mask:0xf bank_mask:0x3
	v_mov_b32_dpp v176, v6 row_ror:8 row_mask:0xf bank_mask:0xf
	v_mov_b32_dpp v177, v7 row_ror:8 row_mask:0xf bank_mask:0xf
	v_mov_b32_dpp v6, v2 row_ror:8 row_mask:0xf bank_mask:0xc
	v_mov_b32_dpp v7, v3 row_ror:8 row_mask:0xf bank_mask:0xc
	v_mov_b32_dpp v2, v176 quad_perm:[0,1,2,3] row_mask:0xf bank_mask:0x3
	v_mov_b32_dpp v3, v177 quad_perm:[0,1,2,3] row_mask:0xf bank_mask:0x3
	s_waitcnt vmcnt(12)
	v_pk_add_f32 v[124:125], v[124:125], v[196:197]
	v_pk_add_f32 v[126:127], v[126:127], v[198:199]
	v_pk_add_f32 v[120:121], v[120:121], v[204:205]
	v_pk_add_f32 v[122:123], v[122:123], v[206:207]
	v_pk_add_f32 v[116:117], v[116:117], v[200:201]
	v_pk_add_f32 v[118:119], v[118:119], v[202:203]
	v_pk_add_f32 v[112:113], v[112:113], v[208:209]
	v_pk_add_f32 v[114:115], v[114:115], v[210:211]
	global_store_dwordx4 v[162:163], v[124:127], off
	global_store_dwordx4 v[162:163], v[116:119], off offset:512
	global_store_dwordx4 v[164:165], v[120:123], off
	global_store_dwordx4 v[164:165], v[112:115], off offset:512
	global_load_dwordx4 v[196:199], v[138:139], off nt
	global_load_dwordx4 v[200:203], v[138:139], off offset:512 nt
	global_load_dwordx4 v[204:207], v[160:161], off nt
	global_load_dwordx4 v[208:211], v[160:161], off offset:512 nt
	v_lshl_add_u64 v[138:139], v[138:139], 0, s[18:19]
	v_lshl_add_u64 v[160:161], v[160:161], 0, s[18:19]
	v_lshl_add_u64 v[162:163], v[162:163], 0, s[18:19]
	v_lshl_add_u64 v[164:165], v[164:165], 0, s[18:19]
	s_waitcnt vmcnt(16)
	v_pk_add_f32 v[108:109], v[108:109], v[212:213]
	v_pk_add_f32 v[110:111], v[110:111], v[214:215]
	v_pk_add_f32 v[104:105], v[104:105], v[220:221]
	v_pk_add_f32 v[106:107], v[106:107], v[222:223]
	v_pk_add_f32 v[92:93], v[92:93], v[216:217]
	v_pk_add_f32 v[94:95], v[94:95], v[218:219]
	v_pk_add_f32 v[88:89], v[88:89], v[224:225]
	v_pk_add_f32 v[90:91], v[90:91], v[226:227]
	global_store_dwordx4 v[162:163], v[108:111], off
	global_store_dwordx4 v[162:163], v[92:95], off offset:512
	global_store_dwordx4 v[164:165], v[104:107], off
	global_store_dwordx4 v[164:165], v[88:91], off offset:512
	global_load_dwordx4 v[212:215], v[138:139], off nt
	global_load_dwordx4 v[216:219], v[138:139], off offset:512 nt
	global_load_dwordx4 v[220:223], v[160:161], off nt
	global_load_dwordx4 v[224:227], v[160:161], off offset:512 nt
	v_lshl_add_u64 v[138:139], v[138:139], 0, s[18:19]
	v_lshl_add_u64 v[160:161], v[160:161], 0, s[18:19]
	v_lshl_add_u64 v[162:163], v[162:163], 0, s[18:19]
	v_lshl_add_u64 v[164:165], v[164:165], 0, s[18:19]
	s_waitcnt vmcnt(20)
; #define PG8_BAR __builtin_amdgcn_s_barrier()
;     __device__ __forceinline__ void operator()(const f32x4 (&acc)[2][2][4][2], const Unit& u, int wr, int wc, int fr, int fq, LAS unsigned char*) const {
;     ...
;             for (int m = 0; m < 4; ++m) { const size_t ro = (size_t)(row0 + ai * HALF + m * 16) * ldc + col0;
; #pragma unroll
;                 for (int bj = 0; bj < 2; ++bj) { const size_t o = ro + bj * HALF; const f32x4 r0 = *(const f32x4*)(res + o), r1 = *(const f32x4*)(res + o + 4);
;                     *(f32x4*)(O + o) = r0 + acc[ai][bj][m][0]; *(f32x4*)(O + o + 4) = r1 + acc[ai][bj][m][1]; } }
; template <class Epi, class Sched>
; __device__ __forceinline__ void gemm_phase(LAS unsigned char* lds, const Gemm g, const Sched& S, const Epi& E) {
;     ...
;         if (wr == 1) PG8_BAR;
	v_pk_add_f32 v[100:101], v[100:101], v[228:229]
	v_pk_add_f32 v[102:103], v[102:103], v[230:231]
	v_pk_add_f32 v[96:97], v[96:97], v[236:237]
	v_pk_add_f32 v[98:99], v[98:99], v[238:239]
	v_pk_add_f32 v[76:77], v[76:77], v[232:233]
	v_pk_add_f32 v[78:79], v[78:79], v[234:235]
	v_pk_add_f32 v[72:73], v[72:73], v[240:241]
	v_pk_add_f32 v[74:75], v[74:75], v[242:243]
	global_store_dwordx4 v[162:163], v[100:103], off
	global_store_dwordx4 v[162:163], v[76:79], off offset:512
	global_store_dwordx4 v[164:165], v[96:99], off
	global_store_dwordx4 v[164:165], v[72:75], off offset:512
	global_load_dwordx4 v[228:231], v[138:139], off nt
	global_load_dwordx4 v[232:235], v[138:139], off offset:512 nt
	global_load_dwordx4 v[236:239], v[160:161], off nt
	global_load_dwordx4 v[240:243], v[160:161], off offset:512 nt
	v_lshl_add_u64 v[138:139], v[138:139], 0, s[18:19]
	v_lshl_add_u64 v[160:161], v[160:161], 0, s[18:19]
	v_lshl_add_u64 v[162:163], v[162:163], 0, s[18:19]
	v_lshl_add_u64 v[164:165], v[164:165], 0, s[18:19]
	s_waitcnt vmcnt(24)
	v_pk_add_f32 v[84:85], v[84:85], v[168:169]
	v_pk_add_f32 v[86:87], v[86:87], v[170:171]
	v_pk_add_f32 v[80:81], v[80:81], v[180:181]
	v_pk_add_f32 v[82:83], v[82:83], v[182:183]
	v_pk_add_f32 v[68:69], v[68:69], v[172:173]
	v_pk_add_f32 v[70:71], v[70:71], v[174:175]
	v_pk_add_f32 v[64:65], v[64:65], v[156:157]
	v_pk_add_f32 v[66:67], v[66:67], v[158:159]
	global_store_dwordx4 v[162:163], v[84:87], off
	global_store_dwordx4 v[162:163], v[68:71], off offset:512
	global_store_dwordx4 v[164:165], v[80:83], off
	global_store_dwordx4 v[164:165], v[64:67], off offset:512
	global_load_dwordx4 v[168:171], v[138:139], off nt
	global_load_dwordx4 v[172:175], v[138:139], off offset:512 nt
	global_load_dwordx4 v[180:183], v[160:161], off nt
	global_load_dwordx4 v[156:159], v[160:161], off offset:512 nt
	v_lshl_add_u64 v[162:163], v[162:163], 0, s[40:41]
	v_lshl_add_u64 v[164:165], v[164:165], 0, s[40:41]
	s_waitcnt vmcnt(24)
	v_pk_add_f32 v[60:61], v[60:61], v[196:197]
	v_pk_add_f32 v[62:63], v[62:63], v[198:199]
	v_pk_add_f32 v[56:57], v[56:57], v[204:205]
	v_pk_add_f32 v[58:59], v[58:59], v[206:207]
	v_pk_add_f32 v[52:53], v[52:53], v[200:201]
	v_pk_add_f32 v[54:55], v[54:55], v[202:203]
	v_pk_add_f32 v[48:49], v[48:49], v[208:209]
	v_pk_add_f32 v[50:51], v[50:51], v[210:211]
	global_store_dwordx4 v[162:163], v[60:63], off
	global_store_dwordx4 v[162:163], v[52:55], off offset:512
	global_store_dwordx4 v[164:165], v[56:59], off
	global_store_dwordx4 v[164:165], v[48:51], off offset:512
	v_lshl_add_u64 v[162:163], v[162:163], 0, s[18:19]
	v_lshl_add_u64 v[164:165], v[164:165], 0, s[18:19]
	s_waitcnt vmcnt(20)
	v_pk_add_f32 v[44:45], v[44:45], v[212:213]
	v_pk_add_f32 v[46:47], v[46:47], v[214:215]
	v_pk_add_f32 v[40:41], v[40:41], v[220:221]
	v_pk_add_f32 v[42:43], v[42:43], v[222:223]
	v_pk_add_f32 v[36:37], v[36:37], v[216:217]
	v_pk_add_f32 v[38:39], v[38:39], v[218:219]
	v_pk_add_f32 v[32:33], v[32:33], v[224:225]
	v_pk_add_f32 v[34:35], v[34:35], v[226:227]
	global_store_dwordx4 v[162:163], v[44:47], off
	global_store_dwordx4 v[162:163], v[36:39], off offset:512
	global_store_dwordx4 v[164:165], v[40:43], off
	global_store_dwordx4 v[164:165], v[32:35], off offset:512
	v_lshl_add_u64 v[162:163], v[162:163], 0, s[18:19]
	v_lshl_add_u64 v[164:165], v[164:165], 0, s[18:19]
	s_waitcnt vmcnt(16)
	v_pk_add_f32 v[28:29], v[28:29], v[228:229]
	v_pk_add_f32 v[30:31], v[30:31], v[230:231]
	v_pk_add_f32 v[24:25], v[24:25], v[236:237]
	v_pk_add_f32 v[26:27], v[26:27], v[238:239]
	v_pk_add_f32 v[20:21], v[20:21], v[232:233]
	v_pk_add_f32 v[22:23], v[22:23], v[234:235]
	v_pk_add_f32 v[16:17], v[16:17], v[240:241]
	v_pk_add_f32 v[18:19], v[18:19], v[242:243]
	global_store_dwordx4 v[162:163], v[28:31], off
	global_store_dwordx4 v[162:163], v[20:23], off offset:512
	global_store_dwordx4 v[164:165], v[24:27], off
	global_store_dwordx4 v[164:165], v[16:19], off offset:512
	v_lshl_add_u64 v[162:163], v[162:163], 0, s[18:19]
	v_lshl_add_u64 v[164:165], v[164:165], 0, s[18:19]
	s_waitcnt vmcnt(12)
	v_pk_add_f32 v[12:13], v[12:13], v[168:169]
	v_pk_add_f32 v[14:15], v[14:15], v[170:171]
	v_pk_add_f32 v[8:9], v[8:9], v[180:181]
	v_pk_add_f32 v[10:11], v[10:11], v[182:183]
	v_pk_add_f32 v[4:5], v[4:5], v[172:173]
	v_pk_add_f32 v[6:7], v[6:7], v[174:175]
	v_pk_add_f32 v[0:1], v[0:1], v[156:157]
	v_pk_add_f32 v[2:3], v[2:3], v[158:159]
	global_store_dwordx4 v[162:163], v[12:15], off
	global_store_dwordx4 v[162:163], v[4:7], off offset:512
	global_store_dwordx4 v[164:165], v[8:11], off
	global_store_dwordx4 v[164:165], v[0:3], off offset:512
	s_mov_b64 s[14:15], -1
	s_and_b64 vcc, exec, s[44:45]
	s_cbranch_vccnz .LBB0_749
	s_andn2_b64 vcc, exec, s[52:53]
	s_cbranch_vccnz .LBB0_748
	s_barrier
	s_branch .LBB0_748

; #define LAS __attribute__((address_space(3)))
;     __device__ __forceinline__ void operator()(const f32x4 (&acc)[2][2][4][2], const Unit& u, int wr, int wc, int fr, int fq, LAS unsigned char* lds) const {
;         const int row0 = u.pm * BM + wr * 64 + fr; const int col0 = u.pn * BM + wc * 32 + 8 * fq;
;         LAS float* part = (LAS float*)(lds + 131072);
;         f32x4 gg[2][2];
; #pragma unroll
;         for (int bj = 0; bj < 2; ++bj)
; #pragma unroll
;             for (int n = 0; n < 2; ++n) gg[bj][n] = *(const f32x4*)(g + col0 + bj * HALF + 4 * n);
; #pragma unroll
;         for (int ai = 0; ai < 2; ++ai)
; #pragma unroll
;             for (int m = 0; m < 4; ++m) { const size_t ro = (size_t)(row0 + ai * HALF + m * 16) * ldc + col0; float ssq = 0.f;
; #pragma unroll
;                 for (int bj = 0; bj < 2; ++bj) { const size_t o = ro + bj * HALF;
;                     const f32x4 r0 = *(const f32x4*)(res + o), r1 = *(const f32x4*)(res + o + 4);
;                     const f32x4 x0 = r0 + acc[ai][bj][m][0], x1 = r1 + acc[ai][bj][m][1];
;                     *(f32x4*)(O + o) = x0; *(f32x4*)(O + o + 4) = x1;
.LBB0_786:
	s_lshl_b32 s46, s4, 8
	v_readlane_b32 s4, v244, 0
	v_readlane_b32 s5, v244, 1
	v_and_b32_e32 v25, 8, v172
	v_sub_u32_e32 v26, v172, v25
	v_add_u32_e32 v26, s46, v26
	v_lshl_or_b32 v27, s56, 8, v174
	v_lshrrev_b32_e32 v25, 1, v25
	v_add_u32_e32 v27, v27, v25
	v_lshl_add_u32 v28, v26, 10, v27
	v_lshlrev_b32_e32 v170, 2, v28
	v_lshlrev_b32_e32 v247, 1, v28
	v_lshlrev_b32_e32 v27, 2, v27
	v_add_u32_e32 v171, 0x8000, v170
	v_add_u32_e32 v24, 0x4000, v247
	v_mov_b32_e32 v177, v170
	v_mov_b32_e32 v195, v171
	v_lshlrev_b32_e32 v54, 2, v193
	v_lshlrev_b32_e32 v55, 2, v194
	global_load_dwordx4 v[180:183], v27, s[4:5]
	global_load_dwordx4 v[166:169], v27, s[4:5] offset:512
	global_load_dwordx4 v[196:199], v170, s[80:81] nt
	global_load_dwordx4 v[200:203], v170, s[80:81] offset:512 nt
	global_load_dwordx4 v[204:207], v171, s[80:81] nt
	global_load_dwordx4 v[208:211], v171, s[80:81] offset:512 nt
	v_add_u32_e32 v170, 0x10000, v170
	v_add_u32_e32 v171, 0x10000, v171
	global_load_dwordx4 v[212:215], v170, s[80:81] nt
	global_load_dwordx4 v[216:219], v170, s[80:81] offset:512 nt
	global_load_dwordx4 v[220:223], v171, s[80:81] nt
	global_load_dwordx4 v[224:227], v171, s[80:81] offset:512 nt
	v_add_u32_e32 v170, 0x10000, v170
	v_add_u32_e32 v171, 0x10000, v171
	global_load_dwordx4 v[228:231], v170, s[80:81] nt
	global_load_dwordx4 v[232:235], v170, s[80:81] offset:512 nt
	global_load_dwordx4 v[236:239], v171, s[80:81] nt
	global_load_dwordx4 v[240:243], v171, s[80:81] offset:512 nt
	v_add_u32_e32 v170, 0x10000, v170
	v_add_u32_e32 v171, 0x10000, v171
	v_mov_b32_dpp v25, v140 row_ror:8 row_mask:0xf bank_mask:0xf
	v_mov_b32_dpp v26, v141 row_ror:8 row_mask:0xf bank_mask:0xf
	v_mov_b32_dpp v140, v136 row_ror:8 row_mask:0xf bank_mask:0xc
	v_mov_b32_dpp v141, v137 row_ror:8 row_mask:0xf bank_mask:0xc
	v_mov_b32_dpp v136, v25 quad_perm:[0,1,2,3] row_mask:0xf bank_mask:0x3
	v_mov_b32_dpp v137, v26 quad_perm:[0,1,2,3] row_mask:0xf bank_mask:0x3
	v_mov_b32_dpp v25, v142 row_ror:8 row_mask:0xf bank_mask:0xf
	v_mov_b32_dpp v26, v143 row_ror:8 row_mask:0xf bank_mask:0xf
	v_mov_b32_dpp v142, v138 row_ror:8 row_mask:0xf bank_mask:0xc
	v_mov_b32_dpp v143, v139 row_ror:8 row_mask:0xf bank_mask:0xc
	v_mov_b32_dpp v138, v25 quad_perm:[0,1,2,3] row_mask:0xf bank_mask:0x3
	v_mov_b32_dpp v139, v26 quad_perm:[0,1,2,3] row_mask:0xf bank_mask:0x3
	v_mov_b32_dpp v25, v132 row_ror:8 row_mask:0xf bank_mask:0xf
	v_mov_b32_dpp v26, v133 row_ror:8 row_mask:0xf bank_mask:0xf
	v_mov_b32_dpp v132, v128 row_ror:8 row_mask:0xf bank_mask:0xc
	v_mov_b32_dpp v133, v129 row_ror:8 row_mask:0xf bank_mask:0xc
	v_mov_b32_dpp v128, v25 quad_perm:[0,1,2,3] row_mask:0xf bank_mask:0x3
	v_mov_b32_dpp v129, v26 quad_perm:[0,1,2,3] row_mask:0xf bank_mask:0x3
	v_mov_b32_dpp v25, v134 row_ror:8 row_mask:0xf bank_mask:0xf
	v_mov_b32_dpp v26, v135 row_ror:8 row_mask:0xf bank_mask:0xf
	v_mov_b32_dpp v134, v130 row_ror:8 row_mask:0xf bank_mask:0xc
	v_mov_b32_dpp v135, v131 row_ror:8 row_mask:0xf bank_mask:0xc
	v_mov_b32_dpp v130, v25 quad_perm:[0,1,2,3] row_mask:0xf bank_mask:0x3
	v_mov_b32_dpp v131, v26 quad_perm:[0,1,2,3] row_mask:0xf bank_mask:0x3
	v_mov_b32_dpp v25, v124 row_ror:8 row_mask:0xf bank_mask:0xf
	v_mov_b32_dpp v26, v125 row_ror:8 row_mask:0xf bank_mask:0xf
	v_mov_b32_dpp v124, v120 row_ror:8 row_mask:0xf bank_mask:0xc
	v_mov_b32_dpp v125, v121 row_ror:8 row_mask:0xf bank_mask:0xc
	v_mov_b32_dpp v120, v25 quad_perm:[0,1,2,3] row_mask:0xf bank_mask:0x3
	v_mov_b32_dpp v121, v26 quad_perm:[0,1,2,3] row_mask:0xf bank_mask:0x3
	v_mov_b32_dpp v25, v126 row_ror:8 row_mask:0xf bank_mask:0xf
	v_mov_b32_dpp v26, v127 row_ror:8 row_mask:0xf bank_mask:0xf
	v_mov_b32_dpp v126, v122 row_ror:8 row_mask:0xf bank_mask:0xc
	v_mov_b32_dpp v127, v123 row_ror:8 row_mask:0xf bank_mask:0xc
	v_mov_b32_dpp v122, v25 quad_perm:[0,1,2,3] row_mask:0xf bank_mask:0x3
	v_mov_b32_dpp v123, v26 quad_perm:[0,1,2,3] row_mask:0xf bank_mask:0x3
	v_mov_b32_dpp v25, v116 row_ror:8 row_mask:0xf bank_mask:0xf
	v_mov_b32_dpp v26, v117 row_ror:8 row_mask:0xf bank_mask:0xf
	v_mov_b32_dpp v116, v112 row_ror:8 row_mask:0xf bank_mask:0xc
	v_mov_b32_dpp v117, v113 row_ror:8 row_mask:0xf bank_mask:0xc
	v_mov_b32_dpp v112, v25 quad_perm:[0,1,2,3] row_mask:0xf bank_mask:0x3
	v_mov_b32_dpp v113, v26 quad_perm:[0,1,2,3] row_mask:0xf bank_mask:0x3
	v_mov_b32_dpp v25, v118 row_ror:8 row_mask:0xf bank_mask:0xf
	v_mov_b32_dpp v26, v119 row_ror:8 row_mask:0xf bank_mask:0xf
	v_mov_b32_dpp v118, v114 row_ror:8 row_mask:0xf bank_mask:0xc
	v_mov_b32_dpp v119, v115 row_ror:8 row_mask:0xf bank_mask:0xc
	v_mov_b32_dpp v114, v25 quad_perm:[0,1,2,3] row_mask:0xf bank_mask:0x3
	v_mov_b32_dpp v115, v26 quad_perm:[0,1,2,3] row_mask:0xf bank_mask:0x3
	v_mov_b32_dpp v25, v108 row_ror:8 row_mask:0xf bank_mask:0xf
	v_mov_b32_dpp v26, v109 row_ror:8 row_mask:0xf bank_mask:0xf
	v_mov_b32_dpp v108, v104 row_ror:8 row_mask:0xf bank_mask:0xc
	v_mov_b32_dpp v109, v105 row_ror:8 row_mask:0xf bank_mask:0xc
	v_mov_b32_dpp v104, v25 quad_perm:[0,1,2,3] row_mask:0xf bank_mask:0x3
	v_mov_b32_dpp v105, v26 quad_perm:[0,1,2,3] row_mask:0xf bank_mask:0x3
	v_mov_b32_dpp v25, v110 row_ror:8 row_mask:0xf bank_mask:0xf
	v_mov_b32_dpp v26, v111 row_ror:8 row_mask:0xf bank_mask:0xf
	v_mov_b32_dpp v110, v106 row_ror:8 row_mask:0xf bank_mask:0xc
	v_mov_b32_dpp v111, v107 row_ror:8 row_mask:0xf bank_mask:0xc
	v_mov_b32_dpp v106, v25 quad_perm:[0,1,2,3] row_mask:0xf bank_mask:0x3
	v_mov_b32_dpp v107, v26 quad_perm:[0,1,2,3] row_mask:0xf bank_mask:0x3
	v_mov_b32_dpp v25, v100 row_ror:8 row_mask:0xf bank_mask:0xf
	v_mov_b32_dpp v26, v101 row_ror:8 row_mask:0xf bank_mask:0xf
; #define LAS __attribute__((address_space(3)))
;     __device__ __forceinline__ void operator()(const f32x4 (&acc)[2][2][4][2], const Unit& u, int wr, int wc, int fr, int fq, LAS unsigned char* lds) const {
;         const int row0 = u.pm * BM + wr * 64 + fr; const int col0 = u.pn * BM + wc * 32 + 8 * fq;
;         LAS float* part = (LAS float*)(lds + 131072);
;         f32x4 gg[2][2];
; #pragma unroll
;         for (int bj = 0; bj < 2; ++bj)
; #pragma unroll
;             for (int n = 0; n < 2; ++n) gg[bj][n] = *(const f32x4*)(g + col0 + bj * HALF + 4 * n);
; #pragma unroll
;         for (int ai = 0; ai < 2; ++ai)
; #pragma unroll
;             for (int m = 0; m < 4; ++m) { const size_t ro = (size_t)(row0 + ai * HALF + m * 16) * ldc + col0; float ssq = 0.f;
; #pragma unroll
;                 for (int bj = 0; bj < 2; ++bj) { const size_t o = ro + bj * HALF;
;                     const f32x4 r0 = *(const f32x4*)(res + o), r1 = *(const f32x4*)(res + o + 4);
;                     const f32x4 x0 = r0 + acc[ai][bj][m][0], x1 = r1 + acc[ai][bj][m][1];
;                     *(f32x4*)(O + o) = x0; *(f32x4*)(O + o + 4) = x1;
	v_mov_b32_dpp v100, v96 row_ror:8 row_mask:0xf bank_mask:0xc
	v_mov_b32_dpp v101, v97 row_ror:8 row_mask:0xf bank_mask:0xc
	v_mov_b32_dpp v96, v25 quad_perm:[0,1,2,3] row_mask:0xf bank_mask:0x3
	v_mov_b32_dpp v97, v26 quad_perm:[0,1,2,3] row_mask:0xf bank_mask:0x3
	v_mov_b32_dpp v25, v102 row_ror:8 row_mask:0xf bank_mask:0xf
	v_mov_b32_dpp v26, v103 row_ror:8 row_mask:0xf bank_mask:0xf
	v_mov_b32_dpp v102, v98 row_ror:8 row_mask:0xf bank_mask:0xc
	v_mov_b32_dpp v103, v99 row_ror:8 row_mask:0xf bank_mask:0xc
	v_mov_b32_dpp v98, v25 quad_perm:[0,1,2,3] row_mask:0xf bank_mask:0x3
	v_mov_b32_dpp v99, v26 quad_perm:[0,1,2,3] row_mask:0xf bank_mask:0x3
	v_mov_b32_dpp v25, v92 row_ror:8 row_mask:0xf bank_mask:0xf
	v_mov_b32_dpp v26, v93 row_ror:8 row_mask:0xf bank_mask:0xf
	v_mov_b32_dpp v92, v88 row_ror:8 row_mask:0xf bank_mask:0xc
	v_mov_b32_dpp v93, v89 row_ror:8 row_mask:0xf bank_mask:0xc
	v_mov_b32_dpp v88, v25 quad_perm:[0,1,2,3] row_mask:0xf bank_mask:0x3
	v_mov_b32_dpp v89, v26 quad_perm:[0,1,2,3] row_mask:0xf bank_mask:0x3
	v_mov_b32_dpp v25, v94 row_ror:8 row_mask:0xf bank_mask:0xf
	v_mov_b32_dpp v26, v95 row_ror:8 row_mask:0xf bank_mask:0xf
	v_mov_b32_dpp v94, v90 row_ror:8 row_mask:0xf bank_mask:0xc
	v_mov_b32_dpp v95, v91 row_ror:8 row_mask:0xf bank_mask:0xc
	v_mov_b32_dpp v90, v25 quad_perm:[0,1,2,3] row_mask:0xf bank_mask:0x3
	v_mov_b32_dpp v91, v26 quad_perm:[0,1,2,3] row_mask:0xf bank_mask:0x3
	v_mov_b32_dpp v25, v84 row_ror:8 row_mask:0xf bank_mask:0xf
	v_mov_b32_dpp v26, v85 row_ror:8 row_mask:0xf bank_mask:0xf
	v_mov_b32_dpp v84, v80 row_ror:8 row_mask:0xf bank_mask:0xc
	v_mov_b32_dpp v85, v81 row_ror:8 row_mask:0xf bank_mask:0xc
	v_mov_b32_dpp v80, v25 quad_perm:[0,1,2,3] row_mask:0xf bank_mask:0x3
	v_mov_b32_dpp v81, v26 quad_perm:[0,1,2,3] row_mask:0xf bank_mask:0x3
	v_mov_b32_dpp v25, v86 row_ror:8 row_mask:0xf bank_mask:0xf
	v_mov_b32_dpp v26, v87 row_ror:8 row_mask:0xf bank_mask:0xf
	v_mov_b32_dpp v86, v82 row_ror:8 row_mask:0xf bank_mask:0xc
	v_mov_b32_dpp v87, v83 row_ror:8 row_mask:0xf bank_mask:0xc
	v_mov_b32_dpp v82, v25 quad_perm:[0,1,2,3] row_mask:0xf bank_mask:0x3
	v_mov_b32_dpp v83, v26 quad_perm:[0,1,2,3] row_mask:0xf bank_mask:0x3
	v_mov_b32_dpp v25, v76 row_ror:8 row_mask:0xf bank_mask:0xf
	v_mov_b32_dpp v26, v77 row_ror:8 row_mask:0xf bank_mask:0xf
	v_mov_b32_dpp v76, v72 row_ror:8 row_mask:0xf bank_mask:0xc
	v_mov_b32_dpp v77, v73 row_ror:8 row_mask:0xf bank_mask:0xc
	v_mov_b32_dpp v72, v25 quad_perm:[0,1,2,3] row_mask:0xf bank_mask:0x3
	v_mov_b32_dpp v73, v26 quad_perm:[0,1,2,3] row_mask:0xf bank_mask:0x3
	v_mov_b32_dpp v25, v78 row_ror:8 row_mask:0xf bank_mask:0xf
	v_mov_b32_dpp v26, v79 row_ror:8 row_mask:0xf bank_mask:0xf
	v_mov_b32_dpp v78, v74 row_ror:8 row_mask:0xf bank_mask:0xc
	v_mov_b32_dpp v79, v75 row_ror:8 row_mask:0xf bank_mask:0xc
	v_mov_b32_dpp v74, v25 quad_perm:[0,1,2,3] row_mask:0xf bank_mask:0x3
	v_mov_b32_dpp v75, v26 quad_perm:[0,1,2,3] row_mask:0xf bank_mask:0x3
	v_mov_b32_dpp v25, v68 row_ror:8 row_mask:0xf bank_mask:0xf
	v_mov_b32_dpp v26, v69 row_ror:8 row_mask:0xf bank_mask:0xf
	v_mov_b32_dpp v68, v64 row_ror:8 row_mask:0xf bank_mask:0xc
	v_mov_b32_dpp v69, v65 row_ror:8 row_mask:0xf bank_mask:0xc
	v_mov_b32_dpp v64, v25 quad_perm:[0,1,2,3] row_mask:0xf bank_mask:0x3
	v_mov_b32_dpp v65, v26 quad_perm:[0,1,2,3] row_mask:0xf bank_mask:0x3
	v_mov_b32_dpp v25, v70 row_ror:8 row_mask:0xf bank_mask:0xf
	v_mov_b32_dpp v26, v71 row_ror:8 row_mask:0xf bank_mask:0xf
	v_mov_b32_dpp v70, v66 row_ror:8 row_mask:0xf bank_mask:0xc
	v_mov_b32_dpp v71, v67 row_ror:8 row_mask:0xf bank_mask:0xc
	v_mov_b32_dpp v66, v25 quad_perm:[0,1,2,3] row_mask:0xf bank_mask:0x3
	v_mov_b32_dpp v67, v26 quad_perm:[0,1,2,3] row_mask:0xf bank_mask:0x3
	v_mov_b32_dpp v25, v60 row_ror:8 row_mask:0xf bank_mask:0xf
	v_mov_b32_dpp v26, v61 row_ror:8 row_mask:0xf bank_mask:0xf
	v_mov_b32_dpp v60, v56 row_ror:8 row_mask:0xf bank_mask:0xc
	v_mov_b32_dpp v61, v57 row_ror:8 row_mask:0xf bank_mask:0xc
	v_mov_b32_dpp v56, v25 quad_perm:[0,1,2,3] row_mask:0xf bank_mask:0x3
	v_mov_b32_dpp v57, v26 quad_perm:[0,1,2,3] row_mask:0xf bank_mask:0x3
	v_mov_b32_dpp v25, v62 row_ror:8 row_mask:0xf bank_mask:0xf
	v_mov_b32_dpp v26, v63 row_ror:8 row_mask:0xf bank_mask:0xf
	v_mov_b32_dpp v62, v58 row_ror:8 row_mask:0xf bank_mask:0xc
	v_mov_b32_dpp v63, v59 row_ror:8 row_mask:0xf bank_mask:0xc
	v_mov_b32_dpp v58, v25 quad_perm:[0,1,2,3] row_mask:0xf bank_mask:0x3
	v_mov_b32_dpp v59, v26 quad_perm:[0,1,2,3] row_mask:0xf bank_mask:0x3
	v_mov_b32_dpp v25, v44 row_ror:8 row_mask:0xf bank_mask:0xf
	v_mov_b32_dpp v26, v45 row_ror:8 row_mask:0xf bank_mask:0xf
	v_mov_b32_dpp v44, v40 row_ror:8 row_mask:0xf bank_mask:0xc
	v_mov_b32_dpp v45, v41 row_ror:8 row_mask:0xf bank_mask:0xc
	v_mov_b32_dpp v40, v25 quad_perm:[0,1,2,3] row_mask:0xf bank_mask:0x3
	v_mov_b32_dpp v41, v26 quad_perm:[0,1,2,3] row_mask:0xf bank_mask:0x3
	v_mov_b32_dpp v25, v46 row_ror:8 row_mask:0xf bank_mask:0xf
	v_mov_b32_dpp v26, v47 row_ror:8 row_mask:0xf bank_mask:0xf
	v_mov_b32_dpp v46, v42 row_ror:8 row_mask:0xf bank_mask:0xc
	v_mov_b32_dpp v47, v43 row_ror:8 row_mask:0xf bank_mask:0xc
	v_mov_b32_dpp v42, v25 quad_perm:[0,1,2,3] row_mask:0xf bank_mask:0x3
	v_mov_b32_dpp v43, v26 quad_perm:[0,1,2,3] row_mask:0xf bank_mask:0x3
	v_mov_b32_dpp v25, v36 row_ror:8 row_mask:0xf bank_mask:0xf
	v_mov_b32_dpp v26, v37 row_ror:8 row_mask:0xf bank_mask:0xf
	v_mov_b32_dpp v36, v32 row_ror:8 row_mask:0xf bank_mask:0xc
	v_mov_b32_dpp v37, v33 row_ror:8 row_mask:0xf bank_mask:0xc
	v_mov_b32_dpp v32, v25 quad_perm:[0,1,2,3] row_mask:0xf bank_mask:0x3
	v_mov_b32_dpp v33, v26 quad_perm:[0,1,2,3] row_mask:0xf bank_mask:0x3
; __device__ __forceinline__ unsigned cvt_pk_bf16(float lo, float hi) { unsigned r; asm volatile("v_cvt_pk_bf16_f32 %0, %1, %2" : "=v"(r) : "v"(lo), "v"(hi)); return r; }
;     __device__ __forceinline__ void operator()(const f32x4 (&acc)[2][2][4][2], const Unit& u, int wr, int wc, int fr, int fq, LAS unsigned char* lds) const {
;     ...
;             for (int m = 0; m < 4; ++m) { const size_t ro = (size_t)(row0 + ai * HALF + m * 16) * ldc + col0; float ssq = 0.f;
; #pragma unroll
;                 for (int bj = 0; bj < 2; ++bj) { const size_t o = ro + bj * HALF;
;                     const f32x4 r0 = *(const f32x4*)(res + o), r1 = *(const f32x4*)(res + o + 4);
;                     const f32x4 x0 = r0 + acc[ai][bj][m][0], x1 = r1 + acc[ai][bj][m][1];
;                     *(f32x4*)(O + o) = x0; *(f32x4*)(O + o + 4) = x1;
;                     u32x4 hb; hb.x = cvt_pk_bf16(x0[0] * gg[bj][0][0], x0[1] * gg[bj][0][1]); hb.y = cvt_pk_bf16(x0[2] * gg[bj][0][2], x0[3] * gg[bj][0][3]);
;                     hb.z = cvt_pk_bf16(x1[0] * gg[bj][1][0], x1[1] * gg[bj][1][1]); hb.w = cvt_pk_bf16(x1[2] * gg[bj][1][2], x1[3] * gg[bj][1][3]);
;                     *(u32x4*)(H + o) = hb;
;                     ssq += ((x0[0] * x0[0] + x0[1] * x0[1]) + (x0[2] * x0[2] + x0[3] * x0[3])) + ((x1[0] * x1[0] + x1[1] * x1[1]) + (x1[2] * x1[2] + x1[3] * x1[3])); }
;                 ssq += __shfl_xor(ssq, 16); ssq += __shfl_xor(ssq, 32);
;                 if (fq == 0) part[(ai * HALF + wr * 64 + m * 16 + fr) * 4 + wc] = ssq; }
	v_mov_b32_dpp v25, v38 row_ror:8 row_mask:0xf bank_mask:0xf
	v_mov_b32_dpp v26, v39 row_ror:8 row_mask:0xf bank_mask:0xf
	v_mov_b32_dpp v38, v34 row_ror:8 row_mask:0xf bank_mask:0xc
	v_mov_b32_dpp v39, v35 row_ror:8 row_mask:0xf bank_mask:0xc
	v_mov_b32_dpp v34, v25 quad_perm:[0,1,2,3] row_mask:0xf bank_mask:0x3
	v_mov_b32_dpp v35, v26 quad_perm:[0,1,2,3] row_mask:0xf bank_mask:0x3
	v_mov_b32_dpp v25, v20 row_ror:8 row_mask:0xf bank_mask:0xf
	v_mov_b32_dpp v26, v21 row_ror:8 row_mask:0xf bank_mask:0xf
	v_mov_b32_dpp v20, v16 row_ror:8 row_mask:0xf bank_mask:0xc
	v_mov_b32_dpp v21, v17 row_ror:8 row_mask:0xf bank_mask:0xc
	v_mov_b32_dpp v16, v25 quad_perm:[0,1,2,3] row_mask:0xf bank_mask:0x3
	v_mov_b32_dpp v17, v26 quad_perm:[0,1,2,3] row_mask:0xf bank_mask:0x3
	v_mov_b32_dpp v25, v22 row_ror:8 row_mask:0xf bank_mask:0xf
	v_mov_b32_dpp v26, v23 row_ror:8 row_mask:0xf bank_mask:0xf
	v_mov_b32_dpp v22, v18 row_ror:8 row_mask:0xf bank_mask:0xc
	v_mov_b32_dpp v23, v19 row_ror:8 row_mask:0xf bank_mask:0xc
	v_mov_b32_dpp v18, v25 quad_perm:[0,1,2,3] row_mask:0xf bank_mask:0x3
	v_mov_b32_dpp v19, v26 quad_perm:[0,1,2,3] row_mask:0xf bank_mask:0x3
	v_mov_b32_dpp v25, v12 row_ror:8 row_mask:0xf bank_mask:0xf
	v_mov_b32_dpp v26, v13 row_ror:8 row_mask:0xf bank_mask:0xf
	v_mov_b32_dpp v12, v8 row_ror:8 row_mask:0xf bank_mask:0xc
	v_mov_b32_dpp v13, v9 row_ror:8 row_mask:0xf bank_mask:0xc
	v_mov_b32_dpp v8, v25 quad_perm:[0,1,2,3] row_mask:0xf bank_mask:0x3
	v_mov_b32_dpp v9, v26 quad_perm:[0,1,2,3] row_mask:0xf bank_mask:0x3
	v_mov_b32_dpp v25, v14 row_ror:8 row_mask:0xf bank_mask:0xf
	v_mov_b32_dpp v26, v15 row_ror:8 row_mask:0xf bank_mask:0xf
	v_mov_b32_dpp v14, v10 row_ror:8 row_mask:0xf bank_mask:0xc
	v_mov_b32_dpp v15, v11 row_ror:8 row_mask:0xf bank_mask:0xc
	v_mov_b32_dpp v10, v25 quad_perm:[0,1,2,3] row_mask:0xf bank_mask:0x3
	v_mov_b32_dpp v11, v26 quad_perm:[0,1,2,3] row_mask:0xf bank_mask:0x3
	v_mov_b32_dpp v25, v4 row_ror:8 row_mask:0xf bank_mask:0xf
	v_mov_b32_dpp v26, v5 row_ror:8 row_mask:0xf bank_mask:0xf
	v_mov_b32_dpp v4, v0 row_ror:8 row_mask:0xf bank_mask:0xc
	v_mov_b32_dpp v5, v1 row_ror:8 row_mask:0xf bank_mask:0xc
	v_mov_b32_dpp v0, v25 quad_perm:[0,1,2,3] row_mask:0xf bank_mask:0x3
	v_mov_b32_dpp v1, v26 quad_perm:[0,1,2,3] row_mask:0xf bank_mask:0x3
	v_mov_b32_dpp v25, v6 row_ror:8 row_mask:0xf bank_mask:0xf
	v_mov_b32_dpp v26, v7 row_ror:8 row_mask:0xf bank_mask:0xf
	v_mov_b32_dpp v6, v2 row_ror:8 row_mask:0xf bank_mask:0xc
	v_mov_b32_dpp v7, v3 row_ror:8 row_mask:0xf bank_mask:0xc
	v_mov_b32_dpp v2, v25 quad_perm:[0,1,2,3] row_mask:0xf bank_mask:0x3
	v_mov_b32_dpp v3, v26 quad_perm:[0,1,2,3] row_mask:0xf bank_mask:0x3
	s_waitcnt vmcnt(8)
	v_pk_add_f32 v[140:141], v[140:141], v[196:197]
	v_pk_add_f32 v[142:143], v[142:143], v[198:199]
	v_pk_add_f32 v[132:133], v[132:133], v[200:201]
	v_pk_add_f32 v[134:135], v[134:135], v[202:203]
	v_pk_add_f32 v[136:137], v[136:137], v[204:205]
	v_pk_add_f32 v[138:139], v[138:139], v[206:207]
	v_pk_add_f32 v[128:129], v[128:129], v[208:209]
	v_pk_add_f32 v[130:131], v[130:131], v[210:211]
	global_store_dwordx4 v177, v[140:143], s[76:77]
	global_store_dwordx4 v177, v[132:135], s[76:77] offset:512
	global_store_dwordx4 v195, v[136:139], s[76:77]
	global_store_dwordx4 v195, v[128:131], s[76:77] offset:512
	global_load_dwordx4 v[196:199], v170, s[80:81] nt
	global_load_dwordx4 v[200:203], v170, s[80:81] offset:512 nt
	global_load_dwordx4 v[204:207], v171, s[80:81] nt
	global_load_dwordx4 v[208:211], v171, s[80:81] offset:512 nt
	v_add_u32_e32 v170, 0x50000, v170
	v_add_u32_e32 v171, 0x50000, v171
	v_mul_f32_e32 v27, v180, v140
	v_mul_f32_e32 v28, v181, v141
	v_cvt_pk_bf16_f32 v30, v27, v28
	v_mul_f32_e32 v27, v182, v142
	v_mul_f32_e32 v28, v183, v143
	v_cvt_pk_bf16_f32 v31, v27, v28
	global_store_dwordx2 v247, v[30:31], s[88:89]
	v_mul_f32_e32 v27, v166, v132
	v_mul_f32_e32 v28, v167, v133
	v_cvt_pk_bf16_f32 v48, v27, v28
	v_mul_f32_e32 v27, v168, v134
	v_mul_f32_e32 v28, v169, v135
	v_cvt_pk_bf16_f32 v49, v27, v28
	global_store_dwordx2 v247, v[48:49], s[88:89] offset:256
	v_mul_f32_e32 v27, v180, v136
	v_mul_f32_e32 v28, v181, v137
	v_cvt_pk_bf16_f32 v30, v27, v28
	v_mul_f32_e32 v27, v182, v138
	v_mul_f32_e32 v28, v183, v139
	v_cvt_pk_bf16_f32 v31, v27, v28
	global_store_dwordx2 v24, v[30:31], s[88:89]
	v_mul_f32_e32 v27, v166, v128
	v_mul_f32_e32 v28, v167, v129
	v_cvt_pk_bf16_f32 v48, v27, v28
	v_mul_f32_e32 v27, v168, v130
	v_mul_f32_e32 v28, v169, v131
	v_cvt_pk_bf16_f32 v49, v27, v28
	global_store_dwordx2 v24, v[48:49], s[88:89] offset:256
	v_mul_f32_e32 v50, v141, v141
	v_mul_f32_e32 v29, v143, v143
	v_fmac_f32_e32 v50, v140, v140
	v_fmac_f32_e32 v29, v142, v142
	v_add_f32_e32 v50, v50, v29
	v_mul_f32_e32 v51, v137, v137
	v_mul_f32_e32 v29, v139, v139
	v_fmac_f32_e32 v51, v136, v136
	v_fmac_f32_e32 v29, v138, v138
	v_add_f32_e32 v51, v51, v29
	v_mul_f32_e32 v52, v133, v133
	v_mul_f32_e32 v29, v135, v135
	v_fmac_f32_e32 v52, v132, v132
	v_fmac_f32_e32 v29, v134, v134
	v_add_f32_e32 v52, v52, v29
	v_mul_f32_e32 v53, v129, v129
	v_mul_f32_e32 v29, v131, v131
	v_fmac_f32_e32 v53, v128, v128
	v_fmac_f32_e32 v29, v130, v130
	v_add_f32_e32 v53, v53, v29
	v_add_f32_dpp v27, v50, v50 row_ror:8 row_mask:0xf bank_mask:0x3
	v_add_f32_dpp v28, v52, v52 row_ror:8 row_mask:0xf bank_mask:0x3
	v_add_f32_dpp v27, v51, v51 row_ror:8 row_mask:0xf bank_mask:0xc
	v_add_f32_dpp v28, v53, v53 row_ror:8 row_mask:0xf bank_mask:0xc
	v_add_f32_e32 v27, v27, v28
	ds_bpermute_b32 v29, v54, v27
	s_waitcnt lgkmcnt(0)
	v_add_f32_e32 v27, v27, v29
	ds_bpermute_b32 v29, v55, v27
	s_waitcnt lgkmcnt(0)
; __device__ __forceinline__ unsigned cvt_pk_bf16(float lo, float hi) { unsigned r; asm volatile("v_cvt_pk_bf16_f32 %0, %1, %2" : "=v"(r) : "v"(lo), "v"(hi)); return r; }
;     __device__ __forceinline__ void operator()(const f32x4 (&acc)[2][2][4][2], const Unit& u, int wr, int wc, int fr, int fq, LAS unsigned char* lds) const {
;     ...
;             for (int m = 0; m < 4; ++m) { const size_t ro = (size_t)(row0 + ai * HALF + m * 16) * ldc + col0; float ssq = 0.f;
; #pragma unroll
;                 for (int bj = 0; bj < 2; ++bj) { const size_t o = ro + bj * HALF;
;                     const f32x4 r0 = *(const f32x4*)(res + o), r1 = *(const f32x4*)(res + o + 4);
;                     const f32x4 x0 = r0 + acc[ai][bj][m][0], x1 = r1 + acc[ai][bj][m][1];
;                     *(f32x4*)(O + o) = x0; *(f32x4*)(O + o + 4) = x1;
;                     u32x4 hb; hb.x = cvt_pk_bf16(x0[0] * gg[bj][0][0], x0[1] * gg[bj][0][1]); hb.y = cvt_pk_bf16(x0[2] * gg[bj][0][2], x0[3] * gg[bj][0][3]);
;                     hb.z = cvt_pk_bf16(x1[0] * gg[bj][1][0], x1[1] * gg[bj][1][1]); hb.w = cvt_pk_bf16(x1[2] * gg[bj][1][2], x1[3] * gg[bj][1][3]);
;                     *(u32x4*)(H + o) = hb;
;                     ssq += ((x0[0] * x0[0] + x0[1] * x0[1]) + (x0[2] * x0[2] + x0[3] * x0[3])) + ((x1[0] * x1[0] + x1[1] * x1[1]) + (x1[2] * x1[2] + x1[3] * x1[3])); }
;                 ssq += __shfl_xor(ssq, 16); ssq += __shfl_xor(ssq, 32);
;                 if (fq == 0) part[(ai * HALF + wr * 64 + m * 16 + fr) * 4 + wc] = ssq; }
	v_add_f32_e32 v27, v27, v29
	s_and_saveexec_b64 s[14:15], s[42:43]
	ds_write_b32 v176, v27
	s_or_b64 exec, exec, s[14:15]
	v_add_u32_e32 v177, 0x10000, v177
	v_add_u32_e32 v195, 0x10000, v195
	v_add_u32_e32 v247, 0x8000, v247
	v_add_u32_e32 v24, 0x8000, v24
	s_waitcnt vmcnt(16)
	v_pk_add_f32 v[124:125], v[124:125], v[212:213]
	v_pk_add_f32 v[126:127], v[126:127], v[214:215]
	v_pk_add_f32 v[116:117], v[116:117], v[216:217]
	v_pk_add_f32 v[118:119], v[118:119], v[218:219]
	v_pk_add_f32 v[120:121], v[120:121], v[220:221]
	v_pk_add_f32 v[122:123], v[122:123], v[222:223]
	v_pk_add_f32 v[112:113], v[112:113], v[224:225]
	v_pk_add_f32 v[114:115], v[114:115], v[226:227]
	global_store_dwordx4 v177, v[124:127], s[76:77]
	global_store_dwordx4 v177, v[116:119], s[76:77] offset:512
	global_store_dwordx4 v195, v[120:123], s[76:77]
	global_store_dwordx4 v195, v[112:115], s[76:77] offset:512
	global_load_dwordx4 v[212:215], v170, s[80:81] nt
	global_load_dwordx4 v[216:219], v170, s[80:81] offset:512 nt
	global_load_dwordx4 v[220:223], v171, s[80:81] nt
	global_load_dwordx4 v[224:227], v171, s[80:81] offset:512 nt
	v_add_u32_e32 v170, 0x10000, v170
	v_add_u32_e32 v171, 0x10000, v171
	v_mul_f32_e32 v27, v180, v124
	v_mul_f32_e32 v28, v181, v125
	v_cvt_pk_bf16_f32 v30, v27, v28
	v_mul_f32_e32 v27, v182, v126
	v_mul_f32_e32 v28, v183, v127
	v_cvt_pk_bf16_f32 v31, v27, v28
	global_store_dwordx2 v247, v[30:31], s[88:89]
	v_mul_f32_e32 v27, v166, v116
	v_mul_f32_e32 v28, v167, v117
	v_cvt_pk_bf16_f32 v48, v27, v28
	v_mul_f32_e32 v27, v168, v118
	v_mul_f32_e32 v28, v169, v119
	v_cvt_pk_bf16_f32 v49, v27, v28
	global_store_dwordx2 v247, v[48:49], s[88:89] offset:256
	v_mul_f32_e32 v27, v180, v120
	v_mul_f32_e32 v28, v181, v121
	v_cvt_pk_bf16_f32 v30, v27, v28
	v_mul_f32_e32 v27, v182, v122
	v_mul_f32_e32 v28, v183, v123
	v_cvt_pk_bf16_f32 v31, v27, v28
	global_store_dwordx2 v24, v[30:31], s[88:89]
	v_mul_f32_e32 v27, v166, v112
	v_mul_f32_e32 v28, v167, v113
	v_cvt_pk_bf16_f32 v48, v27, v28
	v_mul_f32_e32 v27, v168, v114
	v_mul_f32_e32 v28, v169, v115
	v_cvt_pk_bf16_f32 v49, v27, v28
	global_store_dwordx2 v24, v[48:49], s[88:89] offset:256
	v_mul_f32_e32 v50, v125, v125
	v_mul_f32_e32 v29, v127, v127
	v_fmac_f32_e32 v50, v124, v124
	v_fmac_f32_e32 v29, v126, v126
	v_add_f32_e32 v50, v50, v29
	v_mul_f32_e32 v51, v121, v121
	v_mul_f32_e32 v29, v123, v123
	v_fmac_f32_e32 v51, v120, v120
	v_fmac_f32_e32 v29, v122, v122
	v_add_f32_e32 v51, v51, v29
	v_mul_f32_e32 v52, v117, v117
	v_mul_f32_e32 v29, v119, v119
	v_fmac_f32_e32 v52, v116, v116
	v_fmac_f32_e32 v29, v118, v118
	v_add_f32_e32 v52, v52, v29
	v_mul_f32_e32 v53, v113, v113
	v_mul_f32_e32 v29, v115, v115
	v_fmac_f32_e32 v53, v112, v112
	v_fmac_f32_e32 v29, v114, v114
	v_add_f32_e32 v53, v53, v29
	v_add_f32_dpp v27, v50, v50 row_ror:8 row_mask:0xf bank_mask:0x3
	v_add_f32_dpp v28, v52, v52 row_ror:8 row_mask:0xf bank_mask:0x3
	v_add_f32_dpp v27, v51, v51 row_ror:8 row_mask:0xf bank_mask:0xc
	v_add_f32_dpp v28, v53, v53 row_ror:8 row_mask:0xf bank_mask:0xc
	v_add_f32_e32 v27, v27, v28
	ds_bpermute_b32 v29, v54, v27
	s_waitcnt lgkmcnt(0)
	v_add_f32_e32 v27, v27, v29
	ds_bpermute_b32 v29, v55, v27
	s_waitcnt lgkmcnt(0)
	v_add_f32_e32 v27, v27, v29
	s_and_saveexec_b64 s[14:15], s[42:43]
	ds_write_b32 v176, v27 offset:256
	s_or_b64 exec, exec, s[14:15]
	v_add_u32_e32 v177, 0x10000, v177
	v_add_u32_e32 v195, 0x10000, v195
	v_add_u32_e32 v247, 0x8000, v247
	v_add_u32_e32 v24, 0x8000, v24
	s_waitcnt vmcnt(24)
	v_pk_add_f32 v[108:109], v[108:109], v[228:229]
	v_pk_add_f32 v[110:111], v[110:111], v[230:231]
	v_pk_add_f32 v[100:101], v[100:101], v[232:233]
	v_pk_add_f32 v[102:103], v[102:103], v[234:235]
	v_pk_add_f32 v[104:105], v[104:105], v[236:237]
	v_pk_add_f32 v[106:107], v[106:107], v[238:239]
	v_pk_add_f32 v[96:97], v[96:97], v[240:241]
	v_pk_add_f32 v[98:99], v[98:99], v[242:243]
	global_store_dwordx4 v177, v[108:111], s[76:77]
	global_store_dwordx4 v177, v[100:103], s[76:77] offset:512
	global_store_dwordx4 v195, v[104:107], s[76:77]
	global_store_dwordx4 v195, v[96:99], s[76:77] offset:512
	global_load_dwordx4 v[228:231], v170, s[80:81] nt
	global_load_dwordx4 v[232:235], v170, s[80:81] offset:512 nt
	global_load_dwordx4 v[236:239], v171, s[80:81] nt
	global_load_dwordx4 v[240:243], v171, s[80:81] offset:512 nt
	v_add_u32_e32 v170, 0x10000, v170
	v_add_u32_e32 v171, 0x10000, v171
	v_mul_f32_e32 v27, v180, v108
	v_mul_f32_e32 v28, v181, v109
	v_cvt_pk_bf16_f32 v30, v27, v28
	v_mul_f32_e32 v27, v182, v110
	v_mul_f32_e32 v28, v183, v111
	v_cvt_pk_bf16_f32 v31, v27, v28
	global_store_dwordx2 v247, v[30:31], s[88:89]
	v_mul_f32_e32 v27, v166, v100
	v_mul_f32_e32 v28, v167, v101
	v_cvt_pk_bf16_f32 v48, v27, v28
	v_mul_f32_e32 v27, v168, v102
	v_mul_f32_e32 v28, v169, v103
	v_cvt_pk_bf16_f32 v49, v27, v28
	global_store_dwordx2 v247, v[48:49], s[88:89] offset:256
	v_mul_f32_e32 v27, v180, v104
	v_mul_f32_e32 v28, v181, v105
	v_cvt_pk_bf16_f32 v30, v27, v28
	v_mul_f32_e32 v27, v182, v106
	v_mul_f32_e32 v28, v183, v107
	v_cvt_pk_bf16_f32 v31, v27, v28
	global_store_dwordx2 v24, v[30:31], s[88:89]
	v_mul_f32_e32 v27, v166, v96
	v_mul_f32_e32 v28, v167, v97
	v_cvt_pk_bf16_f32 v48, v27, v28
	v_mul_f32_e32 v27, v168, v98
	v_mul_f32_e32 v28, v169, v99
	v_cvt_pk_bf16_f32 v49, v27, v28
	global_store_dwordx2 v24, v[48:49], s[88:89] offset:256
	v_mul_f32_e32 v50, v109, v109
	v_mul_f32_e32 v29, v111, v111
	v_fmac_f32_e32 v50, v108, v108
	v_fmac_f32_e32 v29, v110, v110
	v_add_f32_e32 v50, v50, v29
	v_mul_f32_e32 v51, v105, v105
	v_mul_f32_e32 v29, v107, v107
	v_fmac_f32_e32 v51, v104, v104
	v_fmac_f32_e32 v29, v106, v106
	v_add_f32_e32 v51, v51, v29
	v_mul_f32_e32 v52, v101, v101
	v_mul_f32_e32 v29, v103, v103
	v_fmac_f32_e32 v52, v100, v100
	v_fmac_f32_e32 v29, v102, v102
	v_add_f32_e32 v52, v52, v29
	v_mul_f32_e32 v53, v97, v97
	v_mul_f32_e32 v29, v99, v99
	v_fmac_f32_e32 v53, v96, v96
	v_fmac_f32_e32 v29, v98, v98
	v_add_f32_e32 v53, v53, v29
	v_add_f32_dpp v27, v50, v50 row_ror:8 row_mask:0xf bank_mask:0x3
	v_add_f32_dpp v28, v52, v52 row_ror:8 row_mask:0xf bank_mask:0x3
	v_add_f32_dpp v27, v51, v51 row_ror:8 row_mask:0xf bank_mask:0xc
	v_add_f32_dpp v28, v53, v53 row_ror:8 row_mask:0xf bank_mask:0xc
	v_add_f32_e32 v27, v27, v28
	ds_bpermute_b32 v29, v54, v27
	s_waitcnt lgkmcnt(0)
; __device__ __forceinline__ unsigned cvt_pk_bf16(float lo, float hi) { unsigned r; asm volatile("v_cvt_pk_bf16_f32 %0, %1, %2" : "=v"(r) : "v"(lo), "v"(hi)); return r; }
;     __device__ __forceinline__ void operator()(const f32x4 (&acc)[2][2][4][2], const Unit& u, int wr, int wc, int fr, int fq, LAS unsigned char* lds) const {
;     ...
;             for (int m = 0; m < 4; ++m) { const size_t ro = (size_t)(row0 + ai * HALF + m * 16) * ldc + col0; float ssq = 0.f;
; #pragma unroll
;                 for (int bj = 0; bj < 2; ++bj) { const size_t o = ro + bj * HALF;
;                     const f32x4 r0 = *(const f32x4*)(res + o), r1 = *(const f32x4*)(res + o + 4);
;                     const f32x4 x0 = r0 + acc[ai][bj][m][0], x1 = r1 + acc[ai][bj][m][1];
;                     *(f32x4*)(O + o) = x0; *(f32x4*)(O + o + 4) = x1;
;                     u32x4 hb; hb.x = cvt_pk_bf16(x0[0] * gg[bj][0][0], x0[1] * gg[bj][0][1]); hb.y = cvt_pk_bf16(x0[2] * gg[bj][0][2], x0[3] * gg[bj][0][3]);
;                     hb.z = cvt_pk_bf16(x1[0] * gg[bj][1][0], x1[1] * gg[bj][1][1]); hb.w = cvt_pk_bf16(x1[2] * gg[bj][1][2], x1[3] * gg[bj][1][3]);
;                     *(u32x4*)(H + o) = hb;
;                     ssq += ((x0[0] * x0[0] + x0[1] * x0[1]) + (x0[2] * x0[2] + x0[3] * x0[3])) + ((x1[0] * x1[0] + x1[1] * x1[1]) + (x1[2] * x1[2] + x1[3] * x1[3])); }
;                 ssq += __shfl_xor(ssq, 16); ssq += __shfl_xor(ssq, 32);
;                 if (fq == 0) part[(ai * HALF + wr * 64 + m * 16 + fr) * 4 + wc] = ssq; }
	v_add_f32_e32 v27, v27, v29
	ds_bpermute_b32 v29, v55, v27
	s_waitcnt lgkmcnt(0)
	v_add_f32_e32 v27, v27, v29
	s_and_saveexec_b64 s[14:15], s[42:43]
	ds_write_b32 v176, v27 offset:512
	s_or_b64 exec, exec, s[14:15]
	v_add_u32_e32 v177, 0x10000, v177
	v_add_u32_e32 v195, 0x10000, v195
	v_add_u32_e32 v247, 0x8000, v247
	v_add_u32_e32 v24, 0x8000, v24
	s_waitcnt vmcnt(28)
	v_pk_add_f32 v[92:93], v[92:93], v[196:197]
	v_pk_add_f32 v[94:95], v[94:95], v[198:199]
	v_pk_add_f32 v[84:85], v[84:85], v[200:201]
	v_pk_add_f32 v[86:87], v[86:87], v[202:203]
	v_pk_add_f32 v[88:89], v[88:89], v[204:205]
	v_pk_add_f32 v[90:91], v[90:91], v[206:207]
	v_pk_add_f32 v[80:81], v[80:81], v[208:209]
	v_pk_add_f32 v[82:83], v[82:83], v[210:211]
	global_store_dwordx4 v177, v[92:95], s[76:77]
	global_store_dwordx4 v177, v[84:87], s[76:77] offset:512
	global_store_dwordx4 v195, v[88:91], s[76:77]
	global_store_dwordx4 v195, v[80:83], s[76:77] offset:512
	global_load_dwordx4 v[196:199], v170, s[80:81] nt
	global_load_dwordx4 v[200:203], v170, s[80:81] offset:512 nt
	global_load_dwordx4 v[204:207], v171, s[80:81] nt
	global_load_dwordx4 v[208:211], v171, s[80:81] offset:512 nt
	v_add_u32_e32 v170, 0x10000, v170
	v_add_u32_e32 v171, 0x10000, v171
	v_mul_f32_e32 v27, v180, v92
	v_mul_f32_e32 v28, v181, v93
	v_cvt_pk_bf16_f32 v30, v27, v28
	v_mul_f32_e32 v27, v182, v94
	v_mul_f32_e32 v28, v183, v95
	v_cvt_pk_bf16_f32 v31, v27, v28
	global_store_dwordx2 v247, v[30:31], s[88:89]
	v_mul_f32_e32 v27, v166, v84
	v_mul_f32_e32 v28, v167, v85
	v_cvt_pk_bf16_f32 v48, v27, v28
	v_mul_f32_e32 v27, v168, v86
	v_mul_f32_e32 v28, v169, v87
	v_cvt_pk_bf16_f32 v49, v27, v28
	global_store_dwordx2 v247, v[48:49], s[88:89] offset:256
	v_mul_f32_e32 v27, v180, v88
	v_mul_f32_e32 v28, v181, v89
	v_cvt_pk_bf16_f32 v30, v27, v28
	v_mul_f32_e32 v27, v182, v90
	v_mul_f32_e32 v28, v183, v91
	v_cvt_pk_bf16_f32 v31, v27, v28
	global_store_dwordx2 v24, v[30:31], s[88:89]
	v_mul_f32_e32 v27, v166, v80
	v_mul_f32_e32 v28, v167, v81
	v_cvt_pk_bf16_f32 v48, v27, v28
	v_mul_f32_e32 v27, v168, v82
	v_mul_f32_e32 v28, v169, v83
	v_cvt_pk_bf16_f32 v49, v27, v28
	global_store_dwordx2 v24, v[48:49], s[88:89] offset:256
	v_mul_f32_e32 v50, v93, v93
	v_mul_f32_e32 v29, v95, v95
	v_fmac_f32_e32 v50, v92, v92
	v_fmac_f32_e32 v29, v94, v94
	v_add_f32_e32 v50, v50, v29
	v_mul_f32_e32 v51, v89, v89
	v_mul_f32_e32 v29, v91, v91
	v_fmac_f32_e32 v51, v88, v88
	v_fmac_f32_e32 v29, v90, v90
	v_add_f32_e32 v51, v51, v29
	v_mul_f32_e32 v52, v85, v85
	v_mul_f32_e32 v29, v87, v87
	v_fmac_f32_e32 v52, v84, v84
	v_fmac_f32_e32 v29, v86, v86
	v_add_f32_e32 v52, v52, v29
	v_mul_f32_e32 v53, v81, v81
	v_mul_f32_e32 v29, v83, v83
	v_fmac_f32_e32 v53, v80, v80
	v_fmac_f32_e32 v29, v82, v82
	v_add_f32_e32 v53, v53, v29
	v_add_f32_dpp v27, v50, v50 row_ror:8 row_mask:0xf bank_mask:0x3
	v_add_f32_dpp v28, v52, v52 row_ror:8 row_mask:0xf bank_mask:0x3
	v_add_f32_dpp v27, v51, v51 row_ror:8 row_mask:0xf bank_mask:0xc
	v_add_f32_dpp v28, v53, v53 row_ror:8 row_mask:0xf bank_mask:0xc
	v_add_f32_e32 v27, v27, v28
	ds_bpermute_b32 v29, v54, v27
	s_waitcnt lgkmcnt(0)
	v_add_f32_e32 v27, v27, v29
	ds_bpermute_b32 v29, v55, v27
	s_waitcnt lgkmcnt(0)
	v_add_f32_e32 v27, v27, v29
	s_and_saveexec_b64 s[14:15], s[42:43]
	ds_write_b32 v176, v27 offset:768
	s_or_b64 exec, exec, s[14:15]
	v_add_u32_e32 v177, 0x50000, v177
	v_add_u32_e32 v195, 0x50000, v195
	v_add_u32_e32 v247, 0x28000, v247
	v_add_u32_e32 v24, 0x28000, v24
	s_waitcnt vmcnt(28)
	v_pk_add_f32 v[76:77], v[76:77], v[212:213]
	v_pk_add_f32 v[78:79], v[78:79], v[214:215]
	v_pk_add_f32 v[68:69], v[68:69], v[216:217]
	v_pk_add_f32 v[70:71], v[70:71], v[218:219]
	v_pk_add_f32 v[72:73], v[72:73], v[220:221]
	v_pk_add_f32 v[74:75], v[74:75], v[222:223]
	v_pk_add_f32 v[64:65], v[64:65], v[224:225]
	v_pk_add_f32 v[66:67], v[66:67], v[226:227]
	global_store_dwordx4 v177, v[76:79], s[76:77]
	global_store_dwordx4 v177, v[68:71], s[76:77] offset:512
	global_store_dwordx4 v195, v[72:75], s[76:77]
	global_store_dwordx4 v195, v[64:67], s[76:77] offset:512
	global_load_dwordx4 v[212:215], v170, s[80:81] nt
	global_load_dwordx4 v[216:219], v170, s[80:81] offset:512 nt
	global_load_dwordx4 v[220:223], v171, s[80:81] nt
	global_load_dwordx4 v[224:227], v171, s[80:81] offset:512 nt
	v_mul_f32_e32 v27, v180, v76
	v_mul_f32_e32 v28, v181, v77
	v_cvt_pk_bf16_f32 v30, v27, v28
	v_mul_f32_e32 v27, v182, v78
	v_mul_f32_e32 v28, v183, v79
	v_cvt_pk_bf16_f32 v31, v27, v28
	global_store_dwordx2 v247, v[30:31], s[88:89]
	v_mul_f32_e32 v27, v166, v68
	v_mul_f32_e32 v28, v167, v69
	v_cvt_pk_bf16_f32 v48, v27, v28
	v_mul_f32_e32 v27, v168, v70
	v_mul_f32_e32 v28, v169, v71
	v_cvt_pk_bf16_f32 v49, v27, v28
	global_store_dwordx2 v247, v[48:49], s[88:89] offset:256
	v_mul_f32_e32 v27, v180, v72
	v_mul_f32_e32 v28, v181, v73
	v_cvt_pk_bf16_f32 v30, v27, v28
	v_mul_f32_e32 v27, v182, v74
	v_mul_f32_e32 v28, v183, v75
	v_cvt_pk_bf16_f32 v31, v27, v28
	global_store_dwordx2 v24, v[30:31], s[88:89]
	v_mul_f32_e32 v27, v166, v64
	v_mul_f32_e32 v28, v167, v65
	v_cvt_pk_bf16_f32 v48, v27, v28
	v_mul_f32_e32 v27, v168, v66
	v_mul_f32_e32 v28, v169, v67
	v_cvt_pk_bf16_f32 v49, v27, v28
	global_store_dwordx2 v24, v[48:49], s[88:89] offset:256
	v_mul_f32_e32 v50, v77, v77
	v_mul_f32_e32 v29, v79, v79
	v_fmac_f32_e32 v50, v76, v76
	v_fmac_f32_e32 v29, v78, v78
	v_add_f32_e32 v50, v50, v29
	v_mul_f32_e32 v51, v73, v73
	v_mul_f32_e32 v29, v75, v75
	v_fmac_f32_e32 v51, v72, v72
	v_fmac_f32_e32 v29, v74, v74
	v_add_f32_e32 v51, v51, v29
	v_mul_f32_e32 v52, v69, v69
	v_mul_f32_e32 v29, v71, v71
	v_fmac_f32_e32 v52, v68, v68
	v_fmac_f32_e32 v29, v70, v70
	v_add_f32_e32 v52, v52, v29
	v_mul_f32_e32 v53, v65, v65
	v_mul_f32_e32 v29, v67, v67
	v_fmac_f32_e32 v53, v64, v64
	v_fmac_f32_e32 v29, v66, v66
	v_add_f32_e32 v53, v53, v29
	v_add_f32_dpp v27, v50, v50 row_ror:8 row_mask:0xf bank_mask:0x3
	v_add_f32_dpp v28, v52, v52 row_ror:8 row_mask:0xf bank_mask:0x3
	v_add_f32_dpp v27, v51, v51 row_ror:8 row_mask:0xf bank_mask:0xc
	v_add_f32_dpp v28, v53, v53 row_ror:8 row_mask:0xf bank_mask:0xc
	v_add_f32_e32 v27, v27, v28
	ds_bpermute_b32 v29, v54, v27
	s_waitcnt lgkmcnt(0)
; __device__ __forceinline__ unsigned cvt_pk_bf16(float lo, float hi) { unsigned r; asm volatile("v_cvt_pk_bf16_f32 %0, %1, %2" : "=v"(r) : "v"(lo), "v"(hi)); return r; }
;     __device__ __forceinline__ void operator()(const f32x4 (&acc)[2][2][4][2], const Unit& u, int wr, int wc, int fr, int fq, LAS unsigned char* lds) const {
;     ...
;             for (int m = 0; m < 4; ++m) { const size_t ro = (size_t)(row0 + ai * HALF + m * 16) * ldc + col0; float ssq = 0.f;
; #pragma unroll
;                 for (int bj = 0; bj < 2; ++bj) { const size_t o = ro + bj * HALF;
;                     const f32x4 r0 = *(const f32x4*)(res + o), r1 = *(const f32x4*)(res + o + 4);
;                     const f32x4 x0 = r0 + acc[ai][bj][m][0], x1 = r1 + acc[ai][bj][m][1];
;                     *(f32x4*)(O + o) = x0; *(f32x4*)(O + o + 4) = x1;
;                     u32x4 hb; hb.x = cvt_pk_bf16(x0[0] * gg[bj][0][0], x0[1] * gg[bj][0][1]); hb.y = cvt_pk_bf16(x0[2] * gg[bj][0][2], x0[3] * gg[bj][0][3]);
;                     hb.z = cvt_pk_bf16(x1[0] * gg[bj][1][0], x1[1] * gg[bj][1][1]); hb.w = cvt_pk_bf16(x1[2] * gg[bj][1][2], x1[3] * gg[bj][1][3]);
;                     *(u32x4*)(H + o) = hb;
;                     ssq += ((x0[0] * x0[0] + x0[1] * x0[1]) + (x0[2] * x0[2] + x0[3] * x0[3])) + ((x1[0] * x1[0] + x1[1] * x1[1]) + (x1[2] * x1[2] + x1[3] * x1[3])); }
;                 ssq += __shfl_xor(ssq, 16); ssq += __shfl_xor(ssq, 32);
;                 if (fq == 0) part[(ai * HALF + wr * 64 + m * 16 + fr) * 4 + wc] = ssq; }
	v_add_f32_e32 v27, v27, v29
	ds_bpermute_b32 v29, v55, v27
	s_waitcnt lgkmcnt(0)
	v_add_f32_e32 v27, v27, v29
	s_and_saveexec_b64 s[14:15], s[42:43]
	ds_write_b32 v176, v27 offset:2048
	s_or_b64 exec, exec, s[14:15]
	v_add_u32_e32 v177, 0x10000, v177
	v_add_u32_e32 v195, 0x10000, v195
	v_add_u32_e32 v247, 0x8000, v247
	v_add_u32_e32 v24, 0x8000, v24
	s_waitcnt vmcnt(28)
	v_pk_add_f32 v[60:61], v[60:61], v[228:229]
	v_pk_add_f32 v[62:63], v[62:63], v[230:231]
	v_pk_add_f32 v[44:45], v[44:45], v[232:233]
	v_pk_add_f32 v[46:47], v[46:47], v[234:235]
	v_pk_add_f32 v[56:57], v[56:57], v[236:237]
	v_pk_add_f32 v[58:59], v[58:59], v[238:239]
	v_pk_add_f32 v[40:41], v[40:41], v[240:241]
	v_pk_add_f32 v[42:43], v[42:43], v[242:243]
	global_store_dwordx4 v177, v[60:63], s[76:77]
	global_store_dwordx4 v177, v[44:47], s[76:77] offset:512
	global_store_dwordx4 v195, v[56:59], s[76:77]
	global_store_dwordx4 v195, v[40:43], s[76:77] offset:512
	v_mul_f32_e32 v27, v180, v60
	v_mul_f32_e32 v28, v181, v61
	v_cvt_pk_bf16_f32 v30, v27, v28
	v_mul_f32_e32 v27, v182, v62
	v_mul_f32_e32 v28, v183, v63
	v_cvt_pk_bf16_f32 v31, v27, v28
	global_store_dwordx2 v247, v[30:31], s[88:89]
	v_mul_f32_e32 v27, v166, v44
	v_mul_f32_e32 v28, v167, v45
	v_cvt_pk_bf16_f32 v48, v27, v28
	v_mul_f32_e32 v27, v168, v46
	v_mul_f32_e32 v28, v169, v47
	v_cvt_pk_bf16_f32 v49, v27, v28
	global_store_dwordx2 v247, v[48:49], s[88:89] offset:256
	v_mul_f32_e32 v27, v180, v56
	v_mul_f32_e32 v28, v181, v57
	v_cvt_pk_bf16_f32 v30, v27, v28
	v_mul_f32_e32 v27, v182, v58
	v_mul_f32_e32 v28, v183, v59
	v_cvt_pk_bf16_f32 v31, v27, v28
	global_store_dwordx2 v24, v[30:31], s[88:89]
	v_mul_f32_e32 v27, v166, v40
	v_mul_f32_e32 v28, v167, v41
	v_cvt_pk_bf16_f32 v48, v27, v28
	v_mul_f32_e32 v27, v168, v42
	v_mul_f32_e32 v28, v169, v43
	v_cvt_pk_bf16_f32 v49, v27, v28
	global_store_dwordx2 v24, v[48:49], s[88:89] offset:256
	v_mul_f32_e32 v50, v61, v61
	v_mul_f32_e32 v29, v63, v63
	v_fmac_f32_e32 v50, v60, v60
	v_fmac_f32_e32 v29, v62, v62
	v_add_f32_e32 v50, v50, v29
	v_mul_f32_e32 v51, v57, v57
	v_mul_f32_e32 v29, v59, v59
	v_fmac_f32_e32 v51, v56, v56
	v_fmac_f32_e32 v29, v58, v58
	v_add_f32_e32 v51, v51, v29
	v_mul_f32_e32 v52, v45, v45
	v_mul_f32_e32 v29, v47, v47
	v_fmac_f32_e32 v52, v44, v44
	v_fmac_f32_e32 v29, v46, v46
	v_add_f32_e32 v52, v52, v29
	v_mul_f32_e32 v53, v41, v41
	v_mul_f32_e32 v29, v43, v43
	v_fmac_f32_e32 v53, v40, v40
	v_fmac_f32_e32 v29, v42, v42
	v_add_f32_e32 v53, v53, v29
	v_add_f32_dpp v27, v50, v50 row_ror:8 row_mask:0xf bank_mask:0x3
	v_add_f32_dpp v28, v52, v52 row_ror:8 row_mask:0xf bank_mask:0x3
	v_add_f32_dpp v27, v51, v51 row_ror:8 row_mask:0xf bank_mask:0xc
	v_add_f32_dpp v28, v53, v53 row_ror:8 row_mask:0xf bank_mask:0xc
	v_add_f32_e32 v27, v27, v28
	ds_bpermute_b32 v29, v54, v27
	s_waitcnt lgkmcnt(0)
	v_add_f32_e32 v27, v27, v29
	ds_bpermute_b32 v29, v55, v27
	s_waitcnt lgkmcnt(0)
	v_add_f32_e32 v27, v27, v29
	s_and_saveexec_b64 s[14:15], s[42:43]
	ds_write_b32 v176, v27 offset:2304
	s_or_b64 exec, exec, s[14:15]
	v_add_u32_e32 v177, 0x10000, v177
	v_add_u32_e32 v195, 0x10000, v195
	v_add_u32_e32 v247, 0x8000, v247
	v_add_u32_e32 v24, 0x8000, v24
	s_waitcnt vmcnt(24)
	v_pk_add_f32 v[36:37], v[36:37], v[196:197]
	v_pk_add_f32 v[38:39], v[38:39], v[198:199]
	v_pk_add_f32 v[20:21], v[20:21], v[200:201]
	v_pk_add_f32 v[22:23], v[22:23], v[202:203]
	v_pk_add_f32 v[32:33], v[32:33], v[204:205]
	v_pk_add_f32 v[34:35], v[34:35], v[206:207]
	v_pk_add_f32 v[16:17], v[16:17], v[208:209]
	v_pk_add_f32 v[18:19], v[18:19], v[210:211]
	global_store_dwordx4 v177, v[36:39], s[76:77]
	global_store_dwordx4 v177, v[20:23], s[76:77] offset:512
	global_store_dwordx4 v195, v[32:35], s[76:77]
	global_store_dwordx4 v195, v[16:19], s[76:77] offset:512
	v_mul_f32_e32 v27, v180, v36
	v_mul_f32_e32 v28, v181, v37
	v_cvt_pk_bf16_f32 v30, v27, v28
	v_mul_f32_e32 v27, v182, v38
	v_mul_f32_e32 v28, v183, v39
	v_cvt_pk_bf16_f32 v31, v27, v28
	global_store_dwordx2 v247, v[30:31], s[88:89]
	v_mul_f32_e32 v27, v166, v20
	v_mul_f32_e32 v28, v167, v21
	v_cvt_pk_bf16_f32 v48, v27, v28
	v_mul_f32_e32 v27, v168, v22
	v_mul_f32_e32 v28, v169, v23
	v_cvt_pk_bf16_f32 v49, v27, v28
	global_store_dwordx2 v247, v[48:49], s[88:89] offset:256
	v_mul_f32_e32 v27, v180, v32
	v_mul_f32_e32 v28, v181, v33
	v_cvt_pk_bf16_f32 v30, v27, v28
	v_mul_f32_e32 v27, v182, v34
	v_mul_f32_e32 v28, v183, v35
	v_cvt_pk_bf16_f32 v31, v27, v28
	global_store_dwordx2 v24, v[30:31], s[88:89]
	v_mul_f32_e32 v27, v166, v16
	v_mul_f32_e32 v28, v167, v17
	v_cvt_pk_bf16_f32 v48, v27, v28
	v_mul_f32_e32 v27, v168, v18
	v_mul_f32_e32 v28, v169, v19
	v_cvt_pk_bf16_f32 v49, v27, v28
	global_store_dwordx2 v24, v[48:49], s[88:89] offset:256
	v_mul_f32_e32 v50, v37, v37
	v_mul_f32_e32 v29, v39, v39
	v_fmac_f32_e32 v50, v36, v36
	v_fmac_f32_e32 v29, v38, v38
	v_add_f32_e32 v50, v50, v29
	v_mul_f32_e32 v51, v33, v33
	v_mul_f32_e32 v29, v35, v35
	v_fmac_f32_e32 v51, v32, v32
	v_fmac_f32_e32 v29, v34, v34
	v_add_f32_e32 v51, v51, v29
	v_mul_f32_e32 v52, v21, v21
	v_mul_f32_e32 v29, v23, v23
	v_fmac_f32_e32 v52, v20, v20
	v_fmac_f32_e32 v29, v22, v22
	v_add_f32_e32 v52, v52, v29
	v_mul_f32_e32 v53, v17, v17
	v_mul_f32_e32 v29, v19, v19
	v_fmac_f32_e32 v53, v16, v16
	v_fmac_f32_e32 v29, v18, v18
	v_add_f32_e32 v53, v53, v29
	v_add_f32_dpp v27, v50, v50 row_ror:8 row_mask:0xf bank_mask:0x3
	v_add_f32_dpp v28, v52, v52 row_ror:8 row_mask:0xf bank_mask:0x3
	v_add_f32_dpp v27, v51, v51 row_ror:8 row_mask:0xf bank_mask:0xc
	v_add_f32_dpp v28, v53, v53 row_ror:8 row_mask:0xf bank_mask:0xc
	v_add_f32_e32 v27, v27, v28
	ds_bpermute_b32 v29, v54, v27
	s_waitcnt lgkmcnt(0)
; #define LAS __attribute__((address_space(3)))
; __device__ __forceinline__ unsigned cvt_pk_bf16(float lo, float hi) { unsigned r; asm volatile("v_cvt_pk_bf16_f32 %0, %1, %2" : "=v"(r) : "v"(lo), "v"(hi)); return r; }
;     __device__ __forceinline__ void operator()(const f32x4 (&acc)[2][2][4][2], const Unit& u, int wr, int wc, int fr, int fq, LAS unsigned char* lds) const {
;     ...
;             for (int m = 0; m < 4; ++m) { const size_t ro = (size_t)(row0 + ai * HALF + m * 16) * ldc + col0; float ssq = 0.f;
; #pragma unroll
;                 for (int bj = 0; bj < 2; ++bj) { const size_t o = ro + bj * HALF;
;                     const f32x4 r0 = *(const f32x4*)(res + o), r1 = *(const f32x4*)(res + o + 4);
;                     const f32x4 x0 = r0 + acc[ai][bj][m][0], x1 = r1 + acc[ai][bj][m][1];
;                     *(f32x4*)(O + o) = x0; *(f32x4*)(O + o + 4) = x1;
;                     u32x4 hb; hb.x = cvt_pk_bf16(x0[0] * gg[bj][0][0], x0[1] * gg[bj][0][1]); hb.y = cvt_pk_bf16(x0[2] * gg[bj][0][2], x0[3] * gg[bj][0][3]);
;                     hb.z = cvt_pk_bf16(x1[0] * gg[bj][1][0], x1[1] * gg[bj][1][1]); hb.w = cvt_pk_bf16(x1[2] * gg[bj][1][2], x1[3] * gg[bj][1][3]);
;                     *(u32x4*)(H + o) = hb;
;                     ssq += ((x0[0] * x0[0] + x0[1] * x0[1]) + (x0[2] * x0[2] + x0[3] * x0[3])) + ((x1[0] * x1[0] + x1[1] * x1[1]) + (x1[2] * x1[2] + x1[3] * x1[3])); }
;                 ssq += __shfl_xor(ssq, 16); ssq += __shfl_xor(ssq, 32);
;                 if (fq == 0) part[(ai * HALF + wr * 64 + m * 16 + fr) * 4 + wc] = ssq; }
;         asm volatile("s_waitcnt lgkmcnt(0)" ::: "memory"); __builtin_amdgcn_s_barrier(); asm volatile("" ::: "memory");
;         const int t = threadIdx.x;
;         if (t < 256) { const f32x4 p = *(const LAS f32x4*)(part + t * 4); rss[(size_t)u.pn * NTOK + u.pm * BM + t] = (p[0] + p[1]) + (p[2] + p[3]); }
	v_add_f32_e32 v27, v27, v29
	ds_bpermute_b32 v29, v55, v27
	s_waitcnt lgkmcnt(0)
	v_add_f32_e32 v27, v27, v29
	s_and_saveexec_b64 s[14:15], s[42:43]
	ds_write_b32 v176, v27 offset:2560
	s_or_b64 exec, exec, s[14:15]
	v_add_u32_e32 v177, 0x10000, v177
	v_add_u32_e32 v195, 0x10000, v195
	v_add_u32_e32 v247, 0x8000, v247
	v_add_u32_e32 v24, 0x8000, v24
	s_waitcnt vmcnt(20)
	v_pk_add_f32 v[12:13], v[12:13], v[212:213]
	v_pk_add_f32 v[14:15], v[14:15], v[214:215]
	v_pk_add_f32 v[4:5], v[4:5], v[216:217]
	v_pk_add_f32 v[6:7], v[6:7], v[218:219]
	v_pk_add_f32 v[8:9], v[8:9], v[220:221]
	v_pk_add_f32 v[10:11], v[10:11], v[222:223]
	v_pk_add_f32 v[0:1], v[0:1], v[224:225]
	v_pk_add_f32 v[2:3], v[2:3], v[226:227]
	global_store_dwordx4 v177, v[12:15], s[76:77]
	global_store_dwordx4 v177, v[4:7], s[76:77] offset:512
	global_store_dwordx4 v195, v[8:11], s[76:77]
	global_store_dwordx4 v195, v[0:3], s[76:77] offset:512
	v_mul_f32_e32 v27, v180, v12
	v_mul_f32_e32 v28, v181, v13
	v_cvt_pk_bf16_f32 v30, v27, v28
	v_mul_f32_e32 v27, v182, v14
	v_mul_f32_e32 v28, v183, v15
	v_cvt_pk_bf16_f32 v31, v27, v28
	global_store_dwordx2 v247, v[30:31], s[88:89]
	v_mul_f32_e32 v27, v166, v4
	v_mul_f32_e32 v28, v167, v5
	v_cvt_pk_bf16_f32 v48, v27, v28
	v_mul_f32_e32 v27, v168, v6
	v_mul_f32_e32 v28, v169, v7
	v_cvt_pk_bf16_f32 v49, v27, v28
	global_store_dwordx2 v247, v[48:49], s[88:89] offset:256
	v_mul_f32_e32 v27, v180, v8
	v_mul_f32_e32 v28, v181, v9
	v_cvt_pk_bf16_f32 v30, v27, v28
	v_mul_f32_e32 v27, v182, v10
	v_mul_f32_e32 v28, v183, v11
	v_cvt_pk_bf16_f32 v31, v27, v28
	global_store_dwordx2 v24, v[30:31], s[88:89]
	v_mul_f32_e32 v27, v166, v0
	v_mul_f32_e32 v28, v167, v1
	v_cvt_pk_bf16_f32 v48, v27, v28
	v_mul_f32_e32 v27, v168, v2
	v_mul_f32_e32 v28, v169, v3
	v_cvt_pk_bf16_f32 v49, v27, v28
	global_store_dwordx2 v24, v[48:49], s[88:89] offset:256
	v_mul_f32_e32 v50, v13, v13
	v_mul_f32_e32 v29, v15, v15
	v_fmac_f32_e32 v50, v12, v12
	v_fmac_f32_e32 v29, v14, v14
	v_add_f32_e32 v50, v50, v29
	v_mul_f32_e32 v51, v9, v9
	v_mul_f32_e32 v29, v11, v11
	v_fmac_f32_e32 v51, v8, v8
	v_fmac_f32_e32 v29, v10, v10
	v_add_f32_e32 v51, v51, v29
	v_mul_f32_e32 v52, v5, v5
	v_mul_f32_e32 v29, v7, v7
	v_fmac_f32_e32 v52, v4, v4
	v_fmac_f32_e32 v29, v6, v6
	v_add_f32_e32 v52, v52, v29
	v_mul_f32_e32 v53, v1, v1
	v_mul_f32_e32 v29, v3, v3
	v_fmac_f32_e32 v53, v0, v0
	v_fmac_f32_e32 v29, v2, v2
	v_add_f32_e32 v53, v53, v29
	v_add_f32_dpp v27, v50, v50 row_ror:8 row_mask:0xf bank_mask:0x3
	v_add_f32_dpp v28, v52, v52 row_ror:8 row_mask:0xf bank_mask:0x3
	v_add_f32_dpp v27, v51, v51 row_ror:8 row_mask:0xf bank_mask:0xc
	v_add_f32_dpp v28, v53, v53 row_ror:8 row_mask:0xf bank_mask:0xc
	v_add_f32_e32 v27, v27, v28
	ds_bpermute_b32 v29, v54, v27
	s_waitcnt lgkmcnt(0)
	v_add_f32_e32 v27, v27, v29
	ds_bpermute_b32 v29, v55, v27
	s_waitcnt lgkmcnt(0)
	v_add_f32_e32 v27, v27, v29
	s_and_saveexec_b64 s[14:15], s[42:43]
	ds_write_b32 v176, v27 offset:2816
	s_or_b64 exec, exec, s[14:15]
	s_waitcnt lgkmcnt(0)
	s_barrier
	s_mov_b64 s[14:15], exec
	v_readlane_b32 s4, v246, 6
	v_readlane_b32 s5, v246, 7
	s_and_b64 s[4:5], s[14:15], s[4:5]
	s_mov_b64 exec, s[4:5]
	s_cbranch_execz .LBB0_804
	s_waitcnt lgkmcnt(0)
	ds_read_b128 v[0:3], v189
	s_ashr_i32 s57, s56, 31
	s_ashr_i32 s47, s46, 31
	s_lshl_b64 s[4:5], s[56:57], 16
	v_readlane_b32 s16, v246, 4
	v_readlane_b32 s17, v246, 5
	s_add_u32 s16, s16, s4
	s_addc_u32 s17, s17, s5
	s_lshl_b64 s[4:5], s[46:47], 2
	s_waitcnt lgkmcnt(0)
	v_mov_b32_e32 v4, v1
	v_mov_b32_e32 v5, v2
	v_mov_b32_e32 v1, v3
	s_add_u32 s4, s16, s4
	v_pk_add_f32 v[0:1], v[4:5], v[0:1]
	s_addc_u32 s5, s17, s5
	v_add_f32_e32 v2, v0, v1
	v_lshl_add_u64 v[0:1], v[178:179], 2, s[4:5]
	global_store_dword v[0:1], v2, off
